# GEMM prologue de-serialisation: second group of prologue LDS-DMAs issued before the wait for the first group (15 prologues), on combined+final version
# speedup vs baseline: 1.0080x; 1.0065x over previous
; #define PG8_STAGE(bufoff, gbase, voff) do { _Pragma("unroll") for (int _i = 0; _i < 2; ++_i) \
;         __builtin_amdgcn_global_load_lds((const unsigned*)((const char*)(gbase) + (voff)[_i]), (LAS unsigned*)(lds + (bufoff) + ldsw + _i * 8192), 16, 0, 0); } while (0)
; #define PG8_WAIT_V(n) asm volatile("s_waitcnt vmcnt(" #n ")" ::: "memory")
; #define PG8_BAR __builtin_amdgcn_s_barrier()
; template <class Epi, bool ALIGN_EPI = true>
; __device__ __forceinline__ void gemm_phase(LAS unsigned char* lds, const Gemm g, const Sched& S, const Epi& E) {
;     ...
;     for (int i = 0; i < 2; ++i) { int R, C; stage_rc(tid * 16 + i * 8192, R, C); const int Rb = (R & ~31) + perm32(R & 31);
;         voffA[i] = (unsigned)(R * g.lda + C) * 2u; voffB[i] = (unsigned)(Rb * g.ldb + C) * 2u; }
;     const size_t kstep = (size_t)(BK * 2);
;     const size_t hstepA = (size_t)HALF * g.lda * 2, hstepB = (size_t)HALF * g.ldb * 2;
;     const unsigned ldsw = (unsigned)wid * 1024u;
;     const int aoff = lds_byte(wr * 64 + fr, fq * 8), boff = lds_byte(wc * 32 + fr, fq * 8);
;     ...
;     PG8_STAGE(PG8_SB(0, 0), cB, voffB); PG8_STAGE(PG8_SB(0, 1), cB + hstepB, voffB); PG8_STAGE(PG8_SA(0, 0), cA, voffA); PG8_STAGE(PG8_SA(0, 1), cA + hstepA, voffA);
;     if (wr == 1) PG8_BAR;
;     PG8_WAIT_V(2); PG8_BAR;
;     PG8_STAGE(PG8_SB(1, 0), cB + kstep, voffB); PG8_STAGE(PG8_SA(1, 0), cA + kstep, voffA); PG8_STAGE(PG8_SB(1, 1), cB + hstepB + kstep, voffB);
;     PG8_WAIT_V(6); PG8_BAR;
.LBB0_302:
	v_readlane_b32 s20, v246, 42
	v_readlane_b32 s22, v246, 44
	v_readlane_b32 s23, v246, 45
	s_add_u32 s63, s22, 1.0
	s_addc_u32 s64, s23, 0
	s_add_u32 s6, s22, 0x110000
	s_addc_u32 s7, s23, 0
	s_and_b32 s22, s14, 3
	s_ashr_i32 s14, s17, 31
	s_lshr_b32 s14, s14, 26
	s_add_i32 s14, s17, s14
	s_ashr_i32 s65, s14, 6
	s_lshl_b32 s66, s15, 6
	s_lshl_b32 s19, s15, 13
	s_mov_b64 s[14:15], 0x80
	s_add_i32 m0, s59, 0x18000
	v_lshl_add_u64 v[8:9], v[8:9], 0, s[14:15]
	s_lshl_b32 s23, s22, 12
	s_ashr_i32 s67, s3, 31
	global_load_lds_dwordx4 v[8:9], off
	v_lshl_add_u64 v[6:7], v[6:7], 0, s[14:15]
	s_add_i32 m0, s59, 0x1a000
	s_add_i32 s68, s59, 0x8000
	s_add_i32 s69, s59, 0xa000
	v_readlane_b32 s21, v246, 43
	global_load_lds_dwordx4 v[6:7], off
	v_lshl_add_u64 v[2:3], v[2:3], 0, s[14:15]
	s_mov_b32 m0, s68
	s_add_u32 s20, s42, 0x80080
	global_load_lds_dwordx4 v[2:3], off
	v_lshl_add_u64 v[2:3], v[4:5], 0, s[14:15]
	s_mov_b32 m0, s69
	s_addc_u32 s21, s43, 0
	global_load_lds_dwordx4 v[2:3], off
	s_add_i32 m0, s59, 0x1c000
	v_lshl_add_u64 v[2:3], s[20:21], 0, v[132:133]
	global_load_lds_dwordx4 v[2:3], off
	v_lshl_add_u64 v[2:3], s[20:21], 0, v[136:137]
	s_add_i32 m0, s59, 0x1e000
	s_sext_i32_i16 s75, s16
	global_load_lds_dwordx4 v[2:3], off
	s_waitcnt vmcnt(8)
	s_barrier
	v_and_b32_e32 v2, 48, v10
	v_lshlrev_b32_e32 v3, 6, v10
	s_movk_i32 s16, 0x3c0
	v_and_or_b32 v2, v3, s16, v2
	v_lshlrev_b32_e32 v3, 2, v10
	v_and_b32_e32 v3, 32, v3
	v_bitop3_b32 v4, v2, s19, v3 bitop3:0xde
	v_bitop3_b32 v147, v2, s23, v3 bitop3:0xde
	v_lshlrev_b32_e32 v2, 15, v11
	v_and_b32_e32 v2, 0xffff0000, v2
	v_lshl_add_u32 v2, v12, 12, v2
	v_and_b32_e32 v3, 1, v11
	v_lshl_or_b32 v2, v3, 6, v2
	s_cmp_gt_i32 s17, 63
	v_lshl_add_u32 v140, v13, 1, v2
	v_lshlrev_b32_e32 v2, 15, v14
	s_cselect_b64 s[16:17], -1, 0
	s_add_i32 s70, s65, -2
	v_and_b32_e32 v2, 0xffff0000, v2
	s_waitcnt vmcnt(6)
	s_cmpk_lt_u32 s18, 0x100
	v_lshl_add_u32 v2, v15, 12, v2
	v_and_b32_e32 v3, 1, v14
	s_cselect_b64 s[18:19], -1, 0
	v_lshl_or_b32 v2, v3, 6, v2
	s_add_i32 s72, 0, 0x10000
	s_add_i32 s73, 0, 0x14000
	v_and_b32_e32 v1, 63, v10
	s_lshl_b32 s71, s22, 6
	v_mov_b32_e32 v141, v139
	v_lshl_add_u32 v142, v16, 1, v2
	v_mov_b32_e32 v143, v139
	v_add_u32_e32 v149, s72, v147
	v_add_u32_e32 v151, s73, v147
	v_add_u32_e32 v153, 0, v4
	v_mov_b64_e32 v[144:145], 0xff
	s_barrier
	s_branch .LBB0_305

; #define PG8_STAGE(bufoff, gbase, voff) do { _Pragma("unroll") for (int _i = 0; _i < 2; ++_i) \
;         __builtin_amdgcn_global_load_lds((const unsigned*)((const char*)(gbase) + (voff)[_i]), (LAS unsigned*)(lds + (bufoff) + ldsw + _i * 8192), 16, 0, 0); } while (0)
; #define PG8_WAIT_V(n) asm volatile("s_waitcnt vmcnt(" #n ")" ::: "memory")
; #define PG8_BAR __builtin_amdgcn_s_barrier()
; template <class Epi, bool ALIGN_EPI = true>
; __device__ __forceinline__ void gemm_phase(LAS unsigned char* lds, const Gemm g, const Sched& S, const Epi& E) {
;     ...
;     for (int i = 0; i < 2; ++i) { int R, C; stage_rc(tid * 16 + i * 8192, R, C); const int Rb = (R & ~31) + perm32(R & 31);
;         voffA[i] = (unsigned)(R * g.lda + C) * 2u; voffB[i] = (unsigned)(Rb * g.ldb + C) * 2u; }
;     const size_t kstep = (size_t)(BK * 2);
;     const size_t hstepA = (size_t)HALF * g.lda * 2, hstepB = (size_t)HALF * g.ldb * 2;
;     const unsigned ldsw = (unsigned)wid * 1024u;
;     const int aoff = lds_byte(wr * 64 + fr, fq * 8), boff = lds_byte(wc * 32 + fr, fq * 8);
;     ...
;     PG8_STAGE(PG8_SB(0, 0), cB, voffB); PG8_STAGE(PG8_SB(0, 1), cB + hstepB, voffB); PG8_STAGE(PG8_SA(0, 0), cA, voffA); PG8_STAGE(PG8_SA(0, 1), cA + hstepA, voffA);
;     if (wr == 1) PG8_BAR;
;     PG8_WAIT_V(2); PG8_BAR;
;     PG8_STAGE(PG8_SB(1, 0), cB + kstep, voffB); PG8_STAGE(PG8_SA(1, 0), cA + kstep, voffA); PG8_STAGE(PG8_SB(1, 1), cB + hstepB + kstep, voffB);
;     PG8_WAIT_V(6); PG8_BAR;
.LBB0_376:
	s_and_b32 s20, s20, 7
	s_or_b32 s66, s20, s21
	s_sub_i32 s51, s12, s3
	s_add_u32 s52, s17, 0x45800000
	s_addc_u32 s53, s19, 0
	s_ashr_i32 s17, s16, 31
	s_lshr_b32 s17, s17, 26
	s_add_i32 s17, s16, s17
	s_lshl_b32 s14, s14, 5
	s_ashr_i32 s54, s17, 6
	s_lshl_b32 s55, s15, 6
	s_lshl_b32 s17, s15, 13
	s_and_b32 s56, s14, 0x60
	s_mov_b64 s[14:15], 0x80
	s_add_i32 m0, s47, 0x18000
	v_lshl_add_u64 v[8:9], v[8:9], 0, s[14:15]
	s_lshl_b32 s19, s56, 7
	global_load_lds_dwordx4 v[8:9], off
	v_lshl_add_u64 v[6:7], v[6:7], 0, s[14:15]
	s_add_i32 m0, s47, 0x1a000
	s_add_i32 s57, s47, 0x8000
	s_add_i32 s58, s47, 0xa000
	global_load_lds_dwordx4 v[6:7], off
	v_lshl_add_u64 v[2:3], v[2:3], 0, s[14:15]
	s_mov_b32 m0, s57
	s_add_u32 s20, s36, 0x400080
	global_load_lds_dwordx4 v[2:3], off
	v_lshl_add_u64 v[2:3], v[4:5], 0, s[14:15]
	s_mov_b32 m0, s58
	s_addc_u32 s21, s37, 0
	global_load_lds_dwordx4 v[2:3], off
	s_add_i32 m0, s47, 0x1c000
	v_lshl_add_u64 v[2:3], s[20:21], 0, v[134:135]
	global_load_lds_dwordx4 v[2:3], off
	v_lshl_add_u64 v[2:3], s[20:21], 0, v[130:131]
	s_add_i32 m0, s47, 0x1e000
	s_movk_i32 s20, 0x3c0
	global_load_lds_dwordx4 v[2:3], off
	s_waitcnt vmcnt(8)
	s_barrier
	v_and_b32_e32 v2, 48, v11
	v_lshlrev_b32_e32 v3, 6, v11
	v_and_or_b32 v2, v3, s20, v2
	v_lshlrev_b32_e32 v3, 2, v11
	v_and_b32_e32 v3, 32, v3
	v_bitop3_b32 v4, v2, s17, v3 bitop3:0xde
	v_bitop3_b32 v144, s19, v2, v3 bitop3:0xf6
	v_lshlrev_b32_e32 v2, 15, v15
	v_and_b32_e32 v2, 0xffff0000, v2
	v_lshl_add_u32 v2, v14, 12, v2
	v_and_b32_e32 v3, 1, v15
	v_lshl_or_b32 v2, v3, 6, v2
	s_cmp_gt_i32 s16, 63
	v_lshl_add_u32 v138, v16, 1, v2
	v_lshlrev_b32_e32 v2, 15, v10
	s_cselect_b64 s[16:17], -1, 0
	s_add_i32 s59, s54, -2
	v_and_b32_e32 v2, 0xffff0000, v2
	s_waitcnt vmcnt(6)
	s_cmpk_lt_u32 s18, 0x100
	v_lshl_add_u32 v2, v12, 12, v2
	v_and_b32_e32 v3, 1, v10
	s_cselect_b64 s[18:19], -1, 0
	v_lshl_or_b32 v2, v3, 6, v2
	s_add_i32 s61, 0, 0x10000
	s_add_i32 s62, 0, 0x14000
	v_and_b32_e32 v1, 63, v11
	s_ashr_i32 s60, s51, 31
	v_mov_b32_e32 v139, v135
	v_lshl_add_u32 v140, v13, 1, v2
	v_mov_b32_e32 v141, v135
	v_add_u32_e32 v145, s61, v144
	v_add_u32_e32 v146, s62, v144
	v_add_u32_e32 v147, 0, v4
	v_mov_b64_e32 v[142:143], 0x7f
	s_barrier
	s_waitcnt vmcnt(0)
	s_branch .LBB0_379

; #define PG8_STAGE(bufoff, gbase, voff) do { _Pragma("unroll") for (int _i = 0; _i < 2; ++_i) \
;         __builtin_amdgcn_global_load_lds((const unsigned*)((const char*)(gbase) + (voff)[_i]), (LAS unsigned*)(lds + (bufoff) + ldsw + _i * 8192), 16, 0, 0); } while (0)
; #define PG8_WAIT_V(n) asm volatile("s_waitcnt vmcnt(" #n ")" ::: "memory")
; #define PG8_BAR __builtin_amdgcn_s_barrier()
; template <class Epi, bool ALIGN_EPI = true>
; __device__ __forceinline__ void gemm_phase(LAS unsigned char* lds, const Gemm g, const Sched& S, const Epi& E) {
;     ...
;     for (int i = 0; i < 2; ++i) { int R, C; stage_rc(tid * 16 + i * 8192, R, C); const int Rb = (R & ~31) + perm32(R & 31);
;         voffA[i] = (unsigned)(R * g.lda + C) * 2u; voffB[i] = (unsigned)(Rb * g.ldb + C) * 2u; }
;     const size_t kstep = (size_t)(BK * 2);
;     const size_t hstepA = (size_t)HALF * g.lda * 2, hstepB = (size_t)HALF * g.ldb * 2;
;     const unsigned ldsw = (unsigned)wid * 1024u;
;     const int aoff = lds_byte(wr * 64 + fr, fq * 8), boff = lds_byte(wc * 32 + fr, fq * 8);
;     ...
;     PG8_STAGE(PG8_SB(0, 0), cB, voffB); PG8_STAGE(PG8_SB(0, 1), cB + hstepB, voffB); PG8_STAGE(PG8_SA(0, 0), cA, voffA); PG8_STAGE(PG8_SA(0, 1), cA + hstepA, voffA);
;     if (wr == 1) PG8_BAR;
;     PG8_WAIT_V(2); PG8_BAR;
;     PG8_STAGE(PG8_SB(1, 0), cB + kstep, voffB); PG8_STAGE(PG8_SA(1, 0), cA + kstep, voffA); PG8_STAGE(PG8_SB(1, 1), cB + hstepB + kstep, voffB);
;     PG8_WAIT_V(6); PG8_BAR;
.LBB0_403:
	s_add_u32 s49, s17, 0x41800000
	s_addc_u32 s50, s18, 0
	s_ashr_i32 s17, s15, 31
	s_lshr_b32 s17, s17, 26
	s_add_i32 s17, s15, s17
	s_lshl_b32 s6, s6, 5
	s_ashr_i32 s51, s17, 6
	s_lshl_b32 s52, s7, 6
	s_lshl_b32 s17, s7, 13
	s_and_b32 s53, s6, 0x60
	s_mov_b64 s[6:7], 0x80
	s_add_i32 m0, s45, 0x18000
	v_lshl_add_u64 v[8:9], v[8:9], 0, s[6:7]
	s_lshl_b32 s20, s53, 7
	global_load_lds_dwordx4 v[8:9], off
	v_lshl_add_u64 v[6:7], v[6:7], 0, s[6:7]
	s_add_i32 m0, s45, 0x1a000
	s_add_i32 s54, s45, 0x8000
	s_add_i32 s55, s45, 0xa000
	global_load_lds_dwordx4 v[6:7], off
	v_lshl_add_u64 v[2:3], v[2:3], 0, s[6:7]
	s_mov_b32 m0, s54
	s_add_u32 s18, s34, 0x80080
	global_load_lds_dwordx4 v[2:3], off
	v_lshl_add_u64 v[2:3], v[4:5], 0, s[6:7]
	s_mov_b32 m0, s55
	s_addc_u32 s19, s35, 0
	global_load_lds_dwordx4 v[2:3], off
	s_add_i32 m0, s45, 0x1c000
	v_lshl_add_u64 v[2:3], s[18:19], 0, v[132:133]
	global_load_lds_dwordx4 v[2:3], off
	v_lshl_add_u64 v[2:3], s[18:19], 0, v[136:137]
	s_add_i32 m0, s45, 0x1e000
	s_sext_i32_i8 s63, s14
	global_load_lds_dwordx4 v[2:3], off
	s_waitcnt vmcnt(8)
	s_barrier
	v_and_b32_e32 v2, 48, v10
	v_lshlrev_b32_e32 v3, 6, v10
	s_movk_i32 s14, 0x3c0
	v_and_or_b32 v2, v3, s14, v2
	v_lshlrev_b32_e32 v3, 2, v10
	v_and_b32_e32 v3, 32, v3
	v_bitop3_b32 v4, v2, s17, v3 bitop3:0xde
	v_bitop3_b32 v144, s20, v2, v3 bitop3:0xf6
	v_lshlrev_b32_e32 v2, 18, v11
	v_and_b32_e32 v2, 0xfff80000, v2
	v_lshl_add_u32 v2, v12, 15, v2
	v_and_b32_e32 v3, 1, v11
	v_lshl_or_b32 v2, v3, 6, v2
	s_cmp_gt_i32 s15, 63
	v_lshl_add_u32 v138, v13, 1, v2
	v_lshlrev_b32_e32 v2, 18, v14
	s_cselect_b64 s[14:15], -1, 0
	s_add_i32 s56, s51, -2
	v_and_b32_e32 v2, 0xfff80000, v2
	s_waitcnt vmcnt(6)
	s_cmpk_lt_u32 s16, 0x100
	v_lshl_add_u32 v2, v15, 15, v2
	v_and_b32_e32 v3, 1, v14
	s_cselect_b64 s[16:17], -1, 0
	v_lshl_or_b32 v2, v3, 6, v2
	s_add_i32 s58, 0, 0x10000
	s_add_i32 s59, 0, 0x14000
	v_and_b32_e32 v1, 63, v10
	s_ashr_i32 s57, s3, 31
	v_mov_b32_e32 v139, v133
	v_lshl_add_u32 v140, v16, 1, v2
	v_mov_b32_e32 v141, v133
	v_add_u32_e32 v145, s58, v144
	v_add_u32_e32 v146, s59, v144
	v_add_u32_e32 v147, 0, v4
	v_mov_b64_e32 v[142:143], 0x7f
	s_barrier
	s_branch .LBB0_406

; #define LAS __attribute__((address_space(3)))
; #define PG8_WAIT_V(n) asm volatile("s_waitcnt vmcnt(" #n ")" ::: "memory")
; #define PG8_BAR __builtin_amdgcn_s_barrier()
; template <class Epi, bool ALIGN_EPI = true>
; __device__ __forceinline__ void gemm_phase(LAS unsigned char* lds, const Gemm g, const Sched& S, const Epi& E) {
;     ...
;     for (int i = 0; i < 2; ++i) { int R, C; stage_rc(tid * 16 + i * 8192, R, C); const int Rb = (R & ~31) + perm32(R & 31);
;         voffA[i] = (unsigned)(R * g.lda + C) * 2u; voffB[i] = (unsigned)(Rb * g.ldb + C) * 2u; }
;     const size_t kstep = (size_t)(BK * 2);
;     const size_t hstepA = (size_t)HALF * g.lda * 2, hstepB = (size_t)HALF * g.ldb * 2;
;     const unsigned ldsw = (unsigned)wid * 1024u;
;     const int aoff = lds_byte(wr * 64 + fr, fq * 8), boff = lds_byte(wc * 32 + fr, fq * 8);
;     ...
;     Unit cur, nxt; int ui = 0;
;     if (!S.next(0, cur)) return;
;     if constexpr (Epi::USES_RSTD) {
;         LAS float* T = (LAS float*)(lds + RSTD_OFF);
; #pragma unroll
;         for (int k = 0; k < RSTD_UNITS * 256 / 512; ++k) { const int idx = tid + 512 * k; Unit uu;
;             if (S.next(idx >> 8, uu)) { const float* sp = E.SS + uu.pm * BM + (idx & 255); float ssum = 0.f;
; #pragma unroll
;                 for (int j = 0; j < 8; ++j) ssum += sp[(size_t)j * MROWS];
;                 T[idx] = __builtin_amdgcn_rsqf(ssum * (1.0f / DM) + EPS); } }
;         asm volatile("s_waitcnt lgkmcnt(0)" ::: "memory"); __builtin_amdgcn_s_barrier(); asm volatile("" ::: "memory");
;     }
;     f32x4 acc[2][2][4][2];
; #pragma unroll
;     for (int a = 0; a < 2; ++a)
; #pragma unroll
;         for (int b = 0; b < 2; ++b)
; #pragma unroll
;             for (int m = 0; m < 4; ++m)
; #pragma unroll
;                 for (int n = 0; n < 2; ++n) acc[a][b][m][n] = (f32x4){0.f, 0.f, 0.f, 0.f};
;     bf16x8 At[4][2], B0[2][2], B1[2][2];
;     const char* cA = (const char*)g.A + cur.aoff; const char* cB = (const char*)g.Bt + cur.boff;
;     PG8_STAGE(PG8_SB(0, 0), cB, voffB); PG8_STAGE(PG8_SB(0, 1), cB + hstepB, voffB); PG8_STAGE(PG8_SA(0, 0), cA, voffA); PG8_STAGE(PG8_SA(0, 1), cA + hstepA, voffA);
;     if (wr == 1) PG8_BAR;
;     PG8_WAIT_V(2); PG8_BAR;
;     PG8_STAGE(PG8_SB(1, 0), cB + kstep, voffB); PG8_STAGE(PG8_SA(1, 0), cA + kstep, voffA); PG8_STAGE(PG8_SB(1, 1), cB + hstepB + kstep, voffB);
;     PG8_WAIT_V(6); PG8_BAR;
.LBB0_492:
	v_readlane_b32 s60, v246, 42
	v_readlane_b32 s62, v246, 44
	v_readlane_b32 s63, v246, 45
	s_add_u32 s44, s62, s44
	s_addc_u32 s45, s63, s45
	s_add_u32 s24, s62, s24
	s_addc_u32 s25, s63, s25
	s_add_u32 s31, s62, s20
	s_addc_u32 s34, s63, s21
	s_add_u32 s20, s62, s22
	s_addc_u32 s21, s63, s23
	s_add_u32 s18, s62, s18
	v_writelane_b32 v242, s20, 29
	s_addc_u32 s19, s63, s19
	s_add_u32 s16, s62, s16
	v_writelane_b32 v242, s21, 30
	v_writelane_b32 v242, s18, 31
	s_addc_u32 s17, s63, s17
	s_add_u32 s6, s62, s6
	v_writelane_b32 v242, s19, 32
	v_writelane_b32 v242, s16, 33
	s_addc_u32 s7, s63, s7
	s_add_u32 s33, s62, s4
	v_writelane_b32 v242, s17, 34
	v_writelane_b32 v242, s6, 35
	s_addc_u32 s30, s63, s5
	v_lshl_add_u64 v[10:11], v[10:11], 0, s[8:9]
	v_writelane_b32 v242, s7, 36
	s_add_u32 s6, s62, s14
	s_addc_u32 s7, s63, s15
	s_lshl_b32 s94, s38, 10
	s_lshl_b64 s[4:5], s[94:95], 2
	s_add_u32 s84, s6, s4
	s_addc_u32 s85, s7, s5
	s_ashr_i32 s4, s48, 31
	s_lshr_b32 s4, s4, 26
	s_add_i32 s4, s48, s4
	s_ashr_i32 s46, s4, 6
	s_lshl_b32 s4, s40, 5
	s_and_b32 s89, s4, 0x60
	s_add_i32 m0, s50, 0x18000
	s_lshl_b32 s88, s41, 6
	s_lshl_b32 s6, s41, 13
	s_lshl_b32 s7, s89, 7
	global_load_lds_dwordx4 v[10:11], off
	v_lshl_add_u64 v[8:9], v[8:9], 0, s[8:9]
	s_add_i32 m0, s50, 0x1a000
	s_add_i32 s92, s50, 0x8000
	s_add_i32 s93, s50, 0xa000
	global_load_lds_dwordx4 v[8:9], off
	v_lshl_add_u64 v[4:5], v[4:5], 0, s[8:9]
	s_mov_b32 m0, s92
	s_add_u32 s4, s54, 0x80080
	global_load_lds_dwordx4 v[4:5], off
	v_lshl_add_u64 v[4:5], v[6:7], 0, s[8:9]
	s_mov_b32 m0, s93
	s_addc_u32 s5, s55, 0
	global_load_lds_dwordx4 v[4:5], off
	s_add_i32 m0, s50, 0x1c000
	v_lshl_add_u64 v[4:5], s[4:5], 0, v[152:153]
	global_load_lds_dwordx4 v[4:5], off
	v_lshl_add_u64 v[4:5], s[4:5], 0, v[156:157]
	s_add_i32 m0, s50, 0x1e000
	s_movk_i32 s4, 0x3c0
	global_load_lds_dwordx4 v[4:5], off
	s_waitcnt vmcnt(8)
	s_barrier
	v_and_b32_e32 v4, 48, v12
	v_lshlrev_b32_e32 v5, 6, v12
	v_and_or_b32 v4, v5, s4, v4
	v_lshlrev_b32_e32 v5, 2, v12
	v_and_b32_e32 v5, 32, v5
	v_bitop3_b32 v6, v4, s6, v5 bitop3:0xde
	v_bitop3_b32 v185, s7, v4, v5 bitop3:0xf6
	v_add_u32_e32 v185, 0x10000, v185
	v_lshlrev_b32_e32 v4, 15, v2
	v_and_b32_e32 v4, 0xffff0000, v4
	v_lshl_add_u32 v4, v13, 12, v4
	v_and_b32_e32 v2, 1, v2
	v_lshl_or_b32 v2, v2, 6, v4
	v_readlane_b32 s61, v246, 43
	s_cmp_gt_i32 s48, 63
	v_lshl_add_u32 v158, v14, 1, v2
	v_lshlrev_b32_e32 v2, 15, v15
	s_cselect_b64 s[60:61], -1, 0
	s_add_i32 s94, s46, -2
	v_and_b32_e32 v2, 0xffff0000, v2
	s_cmpk_lt_u32 s47, 0x100
	v_lshl_add_u32 v2, v16, 12, v2
	v_and_b32_e32 v4, 1, v15
	s_waitcnt vmcnt(6)
	s_cselect_b64 s[62:63], -1, 0
	s_and_b32 s4, s47, 0xffffff00
	v_lshl_or_b32 v2, v4, 6, v2
	v_mov_b32_e32 v4, v3
	v_mov_b32_e32 v5, v3
	v_and_b32_e32 v184, 63, v12
	s_add_i32 s47, s4, 0
	v_lshl_add_u32 v160, v17, 1, v2
	v_mov_b32_e32 v2, v3
	v_add_u32_e32 v186, 0, v6
	v_mov_b64_e32 v[8:9], v[4:5]
	v_mov_b64_e32 v[12:13], v[4:5]
	v_mov_b64_e32 v[16:17], v[4:5]
	v_mov_b64_e32 v[20:21], v[4:5]
	v_mov_b64_e32 v[24:25], v[4:5]
	v_mov_b64_e32 v[28:29], v[4:5]
	v_mov_b64_e32 v[32:33], v[4:5]
	v_mov_b64_e32 v[36:37], v[4:5]
	v_mov_b64_e32 v[40:41], v[4:5]
	v_mov_b64_e32 v[44:45], v[4:5]
	v_mov_b64_e32 v[48:49], v[4:5]
	v_mov_b64_e32 v[52:53], v[4:5]
	v_mov_b64_e32 v[56:57], v[4:5]
	v_mov_b64_e32 v[60:61], v[4:5]
	v_mov_b64_e32 v[64:65], v[4:5]
	v_mov_b64_e32 v[68:69], v[4:5]
	v_mov_b64_e32 v[72:73], v[4:5]
	v_mov_b64_e32 v[76:77], v[4:5]
	v_mov_b64_e32 v[80:81], v[4:5]
	v_mov_b64_e32 v[84:85], v[4:5]
	v_mov_b64_e32 v[88:89], v[4:5]
	v_mov_b64_e32 v[92:93], v[4:5]
	v_mov_b64_e32 v[96:97], v[4:5]
	v_mov_b64_e32 v[100:101], v[4:5]
	v_mov_b64_e32 v[104:105], v[4:5]
	v_mov_b64_e32 v[108:109], v[4:5]
	v_mov_b64_e32 v[112:113], v[4:5]
	v_mov_b64_e32 v[116:117], v[4:5]
	v_mov_b64_e32 v[120:121], v[4:5]
	v_mov_b64_e32 v[124:125], v[4:5]
	v_mov_b64_e32 v[128:129], v[4:5]
	v_mov_b64_e32 v[132:133], v[4:5]
	s_mov_b64 s[38:39], s[24:25]
	s_add_i32 s47, s47, 0x20000
	v_mov_b32_e32 v159, v3
	v_mov_b32_e32 v161, v3
	s_mov_b32 s96, 0
	v_mov_b64_e32 v[6:7], v[2:3]
	v_mov_b64_e32 v[10:11], v[2:3]
	v_mov_b64_e32 v[14:15], v[2:3]
	v_mov_b64_e32 v[18:19], v[2:3]
	v_mov_b64_e32 v[22:23], v[2:3]
	v_mov_b64_e32 v[26:27], v[2:3]
	v_mov_b64_e32 v[30:31], v[2:3]
	v_mov_b64_e32 v[34:35], v[2:3]
	v_mov_b64_e32 v[38:39], v[2:3]
	v_mov_b64_e32 v[42:43], v[2:3]
	v_mov_b64_e32 v[46:47], v[2:3]
	v_mov_b64_e32 v[50:51], v[2:3]
	v_mov_b64_e32 v[54:55], v[2:3]
	v_mov_b64_e32 v[58:59], v[2:3]
	v_mov_b64_e32 v[62:63], v[2:3]
	v_mov_b64_e32 v[66:67], v[2:3]
	v_mov_b64_e32 v[70:71], v[2:3]
	v_mov_b64_e32 v[74:75], v[2:3]
	v_mov_b64_e32 v[78:79], v[2:3]
	v_mov_b64_e32 v[82:83], v[2:3]
	v_mov_b64_e32 v[86:87], v[2:3]
	v_mov_b64_e32 v[90:91], v[2:3]
	v_mov_b64_e32 v[94:95], v[2:3]
	v_mov_b64_e32 v[98:99], v[2:3]
	v_mov_b64_e32 v[102:103], v[2:3]
	v_mov_b64_e32 v[106:107], v[2:3]
	v_mov_b64_e32 v[110:111], v[2:3]
	v_mov_b64_e32 v[114:115], v[2:3]
	v_mov_b64_e32 v[118:119], v[2:3]
	v_mov_b64_e32 v[122:123], v[2:3]
	v_mov_b64_e32 v[126:127], v[2:3]
	v_mov_b64_e32 v[130:131], v[2:3]
	s_barrier
	s_branch .LBB0_495

; #define PG8_STAGE(bufoff, gbase, voff) do { _Pragma("unroll") for (int _i = 0; _i < 2; ++_i) \
;         __builtin_amdgcn_global_load_lds((const unsigned*)((const char*)(gbase) + (voff)[_i]), (LAS unsigned*)(lds + (bufoff) + ldsw + _i * 8192), 16, 0, 0); } while (0)
; #define PG8_WAIT_V(n) asm volatile("s_waitcnt vmcnt(" #n ")" ::: "memory")
; #define PG8_BAR __builtin_amdgcn_s_barrier()
; template <class Epi, bool ALIGN_EPI = true>
; __device__ __forceinline__ void gemm_phase(LAS unsigned char* lds, const Gemm g, const Sched& S, const Epi& E) {
;     ...
;     for (int i = 0; i < 2; ++i) { int R, C; stage_rc(tid * 16 + i * 8192, R, C); const int Rb = (R & ~31) + perm32(R & 31);
;         voffA[i] = (unsigned)(R * g.lda + C) * 2u; voffB[i] = (unsigned)(Rb * g.ldb + C) * 2u; }
;     const size_t kstep = (size_t)(BK * 2);
;     const size_t hstepA = (size_t)HALF * g.lda * 2, hstepB = (size_t)HALF * g.ldb * 2;
;     const unsigned ldsw = (unsigned)wid * 1024u;
;     const int aoff = lds_byte(wr * 64 + fr, fq * 8), boff = lds_byte(wc * 32 + fr, fq * 8);
;     ...
;     PG8_STAGE(PG8_SB(0, 0), cB, voffB); PG8_STAGE(PG8_SB(0, 1), cB + hstepB, voffB); PG8_STAGE(PG8_SA(0, 0), cA, voffA); PG8_STAGE(PG8_SA(0, 1), cA + hstepA, voffA);
;     if (wr == 1) PG8_BAR;
;     PG8_WAIT_V(2); PG8_BAR;
;     PG8_STAGE(PG8_SB(1, 0), cB + kstep, voffB); PG8_STAGE(PG8_SA(1, 0), cA + kstep, voffA); PG8_STAGE(PG8_SB(1, 1), cB + hstepB + kstep, voffB);
;     PG8_WAIT_V(6); PG8_BAR;
.LBB0_740:
	v_readlane_b32 s60, v246, 10
	s_add_u32 s52, s54, s6
	v_readlane_b32 s0, v242, 25
	v_readlane_b32 s61, v246, 11
	v_readlane_b32 s62, v246, 12
	v_readlane_b32 s63, v246, 13
	v_readlane_b32 s64, v246, 14
	v_readlane_b32 s65, v246, 15
	s_addc_u32 s53, s55, s7
	s_lshl_b32 s94, s0, 10
	v_readlane_b32 s66, v246, 16
	v_readlane_b32 s67, v246, 17
	v_readlane_b32 s68, v246, 18
	v_readlane_b32 s69, v246, 19
	s_mov_b64 s[60:61], s[64:65]
	s_lshl_b64 s[6:7], s[94:95], 2
	s_mov_b64 s[62:63], s[66:67]
	s_mov_b64 s[64:65], s[68:69]
	s_add_u32 s6, s64, s6
	s_addc_u32 s7, s65, s7
	s_ashr_i32 s18, s14, 31
	s_lshr_b32 s18, s18, 26
	s_lshl_b32 s15, s15, 5
	s_add_i32 s18, s14, s18
	s_and_b32 s58, s15, 0x60
	s_add_i32 m0, s36, 0x18000
	v_lshl_add_u64 v[10:11], v[10:11], 0, s[8:9]
	s_ashr_i32 s54, s18, 6
	s_lshl_b32 s55, s17, 6
	s_lshl_b32 s17, s17, 13
	s_lshl_b32 s15, s58, 7
	global_load_lds_dwordx4 v[10:11], off
	v_lshl_add_u64 v[8:9], v[8:9], 0, s[8:9]
	s_add_i32 m0, s36, 0x1a000
	s_add_i32 s59, s36, 0x8000
	s_add_i32 s60, s36, 0xa000
	global_load_lds_dwordx4 v[8:9], off
	v_lshl_add_u64 v[4:5], v[4:5], 0, s[8:9]
	s_mov_b32 m0, s59
	s_add_u32 s18, s26, 0x10080
	global_load_lds_dwordx4 v[4:5], off
	v_lshl_add_u64 v[4:5], v[6:7], 0, s[8:9]
	s_mov_b32 m0, s60
	s_addc_u32 s19, s27, 0
	global_load_lds_dwordx4 v[4:5], off
	s_add_i32 m0, s36, 0x1c000
	v_lshl_add_u64 v[4:5], s[18:19], 0, v[2:3]
	global_load_lds_dwordx4 v[4:5], off
	v_lshl_add_u64 v[4:5], s[18:19], 0, v[148:149]
	s_add_i32 m0, s36, 0x1e000
	v_and_b32_e32 v162, 63, v18
	global_load_lds_dwordx4 v[4:5], off
	s_waitcnt vmcnt(8)
	s_barrier
	v_lshlrev_b32_e32 v4, 14, v16
	v_and_b32_e32 v4, 0xffff8000, v4
	v_lshl_add_u32 v4, v15, 11, v4
	v_and_b32_e32 v5, 1, v16
	v_lshl_or_b32 v4, v5, 6, v4
	v_and_b32_e32 v19, 48, v18
	v_lshlrev_b32_e32 v20, 6, v18
	s_movk_i32 s10, 0x3c0
	v_lshlrev_b32_e32 v18, 2, v18
	v_lshl_add_u32 v154, v17, 1, v4
	v_lshlrev_b32_e32 v4, 14, v12
	v_and_or_b32 v19, v20, s10, v19
	v_and_b32_e32 v18, 32, v18
	s_cmp_gt_i32 s14, 63
	v_and_b32_e32 v4, 0xffff8000, v4
	v_readlane_b32 s18, v243, 35
	v_bitop3_b32 v163, s15, v19, v18 bitop3:0xf6
	v_add_u32_e32 v163, 0x10000, v163
	s_waitcnt vmcnt(6)
	s_cselect_b64 s[14:15], -1, 0
	s_add_i32 s61, s54, -2
	v_lshl_add_u32 v4, v13, 11, v4
	v_and_b32_e32 v5, 1, v12
	v_readlane_b32 s19, v243, 36
	v_readlane_b32 s1, v242, 26
	v_bitop3_b32 v20, v19, s17, v18 bitop3:0xde
	s_cmpk_lt_u32 s16, 0x100
	v_lshl_or_b32 v4, v5, 6, v4
	s_mov_b32 s64, s18
	v_readlane_b32 s18, v243, 23
	s_mov_b64 s[0:1], s[94:95]
	s_cselect_b64 s[16:17], -1, 0
	v_mov_b32_e32 v155, v3
	v_lshl_add_u32 v156, v14, 1, v4
	v_mov_b32_e32 v157, v3
	s_mov_b32 s49, 0
	v_add_u32_e32 v164, 0, v20
	s_mov_b32 s63, s18
	v_readlane_b32 s70, v246, 20
	v_readlane_b32 s71, v246, 21
	v_readlane_b32 s72, v246, 22
	v_readlane_b32 s73, v246, 23
	v_readlane_b32 s74, v246, 24
	v_readlane_b32 s75, v246, 25
	s_barrier
	v_readlane_b32 s19, v243, 24
	s_branch .LBB0_743

; #define PG8_STAGE(bufoff, gbase, voff) do { _Pragma("unroll") for (int _i = 0; _i < 2; ++_i) \
;         __builtin_amdgcn_global_load_lds((const unsigned*)((const char*)(gbase) + (voff)[_i]), (LAS unsigned*)(lds + (bufoff) + ldsw + _i * 8192), 16, 0, 0); } while (0)
; #define PG8_WAIT_V(n) asm volatile("s_waitcnt vmcnt(" #n ")" ::: "memory")
; #define PG8_BAR __builtin_amdgcn_s_barrier()
; template <class Epi, bool ALIGN_EPI = true>
; __device__ __forceinline__ void gemm_phase(LAS unsigned char* lds, const Gemm g, const Sched& S, const Epi& E) {
;     ...
;     for (int i = 0; i < 2; ++i) { int R, C; stage_rc(tid * 16 + i * 8192, R, C); const int Rb = (R & ~31) + perm32(R & 31);
;         voffA[i] = (unsigned)(R * g.lda + C) * 2u; voffB[i] = (unsigned)(Rb * g.ldb + C) * 2u; }
;     const size_t kstep = (size_t)(BK * 2);
;     const size_t hstepA = (size_t)HALF * g.lda * 2, hstepB = (size_t)HALF * g.ldb * 2;
;     const unsigned ldsw = (unsigned)wid * 1024u;
;     const int aoff = lds_byte(wr * 64 + fr, fq * 8), boff = lds_byte(wc * 32 + fr, fq * 8);
;     ...
;     PG8_STAGE(PG8_SB(0, 0), cB, voffB); PG8_STAGE(PG8_SB(0, 1), cB + hstepB, voffB); PG8_STAGE(PG8_SA(0, 0), cA, voffA); PG8_STAGE(PG8_SA(0, 1), cA + hstepA, voffA);
;     if (wr == 1) PG8_BAR;
;     PG8_WAIT_V(2); PG8_BAR;
;     PG8_STAGE(PG8_SB(1, 0), cB + kstep, voffB); PG8_STAGE(PG8_SA(1, 0), cA + kstep, voffA); PG8_STAGE(PG8_SB(1, 1), cB + hstepB + kstep, voffB);
;     PG8_WAIT_V(6); PG8_BAR;
.LBB0_907:
	v_readlane_b32 s52, v246, 10
	v_readlane_b32 s53, v246, 11
	v_readlane_b32 s54, v246, 12
	v_readlane_b32 s55, v246, 13
	v_readlane_b32 s56, v246, 14
	v_readlane_b32 s57, v246, 15
	s_add_u32 s50, s18, s4
	v_readlane_b32 s58, v246, 16
	v_readlane_b32 s59, v246, 17
	v_readlane_b32 s60, v246, 18
	v_readlane_b32 s61, v246, 19
	s_mov_b64 s[52:53], s[56:57]
	s_addc_u32 s51, s19, s5
	s_lshl_b64 s[4:5], s[94:95], 2
	s_mov_b64 s[54:55], s[58:59]
	s_mov_b64 s[56:57], s[60:61]
	s_add_u32 s4, s56, s4
	s_addc_u32 s5, s57, s5
	s_ashr_i32 s16, s6, 31
	s_lshr_b32 s16, s16, 26
	s_lshl_b32 s7, s7, 5
	s_add_i32 s16, s6, s16
	s_and_b32 s54, s7, 0x60
	s_add_i32 m0, s36, 0x18000
	v_lshl_add_u64 v[10:11], v[10:11], 0, s[8:9]
	s_ashr_i32 s52, s16, 6
	s_lshl_b32 s53, s15, 6
	s_lshl_b32 s15, s15, 13
	s_lshl_b32 s7, s54, 7
	global_load_lds_dwordx4 v[10:11], off
	v_lshl_add_u64 v[8:9], v[8:9], 0, s[8:9]
	s_add_i32 m0, s36, 0x1a000
	s_add_i32 s55, s36, 0x8000
	s_add_i32 s56, s36, 0xa000
	global_load_lds_dwordx4 v[8:9], off
	v_lshl_add_u64 v[4:5], v[4:5], 0, s[8:9]
	s_mov_b32 m0, s55
	s_add_u32 s16, s26, 0x10080
	global_load_lds_dwordx4 v[4:5], off
	v_lshl_add_u64 v[4:5], v[6:7], 0, s[8:9]
	s_mov_b32 m0, s56
	s_addc_u32 s17, s27, 0
	global_load_lds_dwordx4 v[4:5], off
	s_add_i32 m0, s36, 0x1c000
	v_lshl_add_u64 v[4:5], s[16:17], 0, v[2:3]
	global_load_lds_dwordx4 v[4:5], off
	v_lshl_add_u64 v[4:5], s[16:17], 0, v[148:149]
	s_add_i32 m0, s36, 0x1e000
	v_and_b32_e32 v162, 63, v18
	global_load_lds_dwordx4 v[4:5], off
	s_waitcnt vmcnt(8)
	s_barrier
	v_lshlrev_b32_e32 v4, 14, v16
	v_and_b32_e32 v4, 0xffff8000, v4
	v_lshl_add_u32 v4, v15, 11, v4
	v_and_b32_e32 v5, 1, v16
	v_lshl_or_b32 v4, v5, 6, v4
	v_and_b32_e32 v19, 48, v18
	v_lshlrev_b32_e32 v20, 6, v18
	s_movk_i32 s10, 0x3c0
	v_lshlrev_b32_e32 v18, 2, v18
	v_lshl_add_u32 v154, v17, 1, v4
	v_lshlrev_b32_e32 v4, 14, v12
	v_and_or_b32 v19, v20, s10, v19
	v_and_b32_e32 v18, 32, v18
	s_cmp_gt_i32 s6, 63
	v_and_b32_e32 v4, 0xffff8000, v4
	v_readlane_b32 s16, v243, 16
	v_bitop3_b32 v163, s7, v19, v18 bitop3:0xf6
	v_add_u32_e32 v163, 0x10000, v163
	s_waitcnt vmcnt(6)
	s_cselect_b64 s[6:7], -1, 0
	s_add_i32 s57, s52, -2
	v_lshl_add_u32 v4, v13, 11, v4
	v_and_b32_e32 v5, 1, v12
	v_readlane_b32 s17, v243, 17
	v_bitop3_b32 v20, v19, s15, v18 bitop3:0xde
	s_cmpk_lt_u32 s14, 0x100
	v_lshl_or_b32 v4, v5, 6, v4
	s_mov_b32 s60, s16
	v_readlane_b32 s16, v243, 12
	s_cselect_b64 s[14:15], -1, 0
	v_mov_b32_e32 v155, v3
	v_lshl_add_u32 v156, v14, 1, v4
	v_mov_b32_e32 v157, v3
	s_mov_b32 s47, 0
	v_add_u32_e32 v164, 0, v20
	s_mov_b32 s59, s16
	v_readlane_b32 s62, v246, 20
	v_readlane_b32 s63, v246, 21
	v_readlane_b32 s64, v246, 22
	v_readlane_b32 s65, v246, 23
	v_readlane_b32 s66, v246, 24
	v_readlane_b32 s67, v246, 25
	s_barrier
	v_readlane_b32 s17, v243, 13
	s_branch .LBB0_910

; #define LAS __attribute__((address_space(3)))
; #define PG8_WAIT_V(n) asm volatile("s_waitcnt vmcnt(" #n ")" ::: "memory")
; #define PG8_BAR __builtin_amdgcn_s_barrier()
; template <class Epi, bool ALIGN_EPI = true>
; __device__ __forceinline__ void gemm_phase(LAS unsigned char* lds, const Gemm g, const Sched& S, const Epi& E) {
;     ...
;     for (int i = 0; i < 2; ++i) { int R, C; stage_rc(tid * 16 + i * 8192, R, C); const int Rb = (R & ~31) + perm32(R & 31);
;         voffA[i] = (unsigned)(R * g.lda + C) * 2u; voffB[i] = (unsigned)(Rb * g.ldb + C) * 2u; }
;     const size_t kstep = (size_t)(BK * 2);
;     const size_t hstepA = (size_t)HALF * g.lda * 2, hstepB = (size_t)HALF * g.ldb * 2;
;     const unsigned ldsw = (unsigned)wid * 1024u;
;     const int aoff = lds_byte(wr * 64 + fr, fq * 8), boff = lds_byte(wc * 32 + fr, fq * 8);
;     ...
;     Unit cur, nxt; int ui = 0;
;     if (!S.next(0, cur)) return;
;     if constexpr (Epi::USES_RSTD) {
;         LAS float* T = (LAS float*)(lds + RSTD_OFF);
; #pragma unroll
;         for (int k = 0; k < RSTD_UNITS * 256 / 512; ++k) { const int idx = tid + 512 * k; Unit uu;
;             if (S.next(idx >> 8, uu)) { const float* sp = E.SS + uu.pm * BM + (idx & 255); float ssum = 0.f;
; #pragma unroll
;                 for (int j = 0; j < 8; ++j) ssum += sp[(size_t)j * MROWS];
;                 T[idx] = __builtin_amdgcn_rsqf(ssum * (1.0f / DM) + EPS); } }
;         asm volatile("s_waitcnt lgkmcnt(0)" ::: "memory"); __builtin_amdgcn_s_barrier(); asm volatile("" ::: "memory");
;     }
;     f32x4 acc[2][2][4][2];
; #pragma unroll
;     for (int a = 0; a < 2; ++a)
; #pragma unroll
;         for (int b = 0; b < 2; ++b)
; #pragma unroll
;             for (int m = 0; m < 4; ++m)
; #pragma unroll
;                 for (int n = 0; n < 2; ++n) acc[a][b][m][n] = (f32x4){0.f, 0.f, 0.f, 0.f};
;     bf16x8 At[4][2], B0[2][2], B1[2][2];
;     const char* cA = (const char*)g.A + cur.aoff; const char* cB = (const char*)g.Bt + cur.boff;
;     PG8_STAGE(PG8_SB(0, 0), cB, voffB); PG8_STAGE(PG8_SB(0, 1), cB + hstepB, voffB); PG8_STAGE(PG8_SA(0, 0), cA, voffA); PG8_STAGE(PG8_SA(0, 1), cA + hstepA, voffA);
;     if (wr == 1) PG8_BAR;
;     PG8_WAIT_V(2); PG8_BAR;
;     PG8_STAGE(PG8_SB(1, 0), cB + kstep, voffB); PG8_STAGE(PG8_SA(1, 0), cA + kstep, voffA); PG8_STAGE(PG8_SB(1, 1), cB + hstepB + kstep, voffB);
;     PG8_WAIT_V(6); PG8_BAR;
.LBB0_946:
	v_readlane_b32 s36, v246, 42
	v_readlane_b32 s38, v246, 44
	v_readlane_b32 s39, v246, 45
	s_add_u32 s52, s38, s44
	s_addc_u32 s53, s39, s45
	s_add_u32 s24, s38, s24
	s_addc_u32 s25, s39, s25
	v_readlane_b32 s37, v246, 43
	s_add_u32 s36, s38, s20
	s_addc_u32 s37, s39, s21
	s_add_u32 s20, s38, s22
	s_addc_u32 s21, s39, s23
	s_add_u32 s18, s38, s18
	s_addc_u32 s19, s39, s19
	s_add_u32 s16, s38, s16
	s_addc_u32 s17, s39, s17
	s_add_u32 s6, s38, s6
	s_addc_u32 s7, s39, s7
	s_add_u32 s54, s38, s4
	s_addc_u32 s44, s39, s5
	s_add_u32 s4, s38, s14
	s_addc_u32 s5, s39, s15
	s_lshl_b64 s[0:1], s[0:1], 2
	s_mov_b64 s[38:39], s[52:53]
	s_add_u32 s52, s4, s0
	s_addc_u32 s53, s5, s1
	s_ashr_i32 s0, s56, 31
	s_lshr_b32 s0, s0, 26
	s_add_i32 s0, s56, s0
	s_ashr_i32 s31, s0, 6
	s_lshl_b32 s0, s30, 5
	s_and_b32 s45, s0, 0x60
	s_add_i32 m0, s48, 0x18000
	v_lshl_add_u64 v[10:11], v[10:11], 0, s[8:9]
	s_lshl_b32 s34, s33, 6
	s_lshl_b32 s4, s33, 13
	s_lshl_b32 s5, s45, 7
	global_load_lds_dwordx4 v[10:11], off
	v_lshl_add_u64 v[8:9], v[8:9], 0, s[8:9]
	s_add_i32 m0, s48, 0x1a000
	s_add_i32 s30, s48, 0x8000
	s_add_i32 s33, s48, 0xa000
	global_load_lds_dwordx4 v[8:9], off
	v_lshl_add_u64 v[4:5], v[4:5], 0, s[8:9]
	s_mov_b32 m0, s30
	s_add_u32 s0, s40, 0x80080
	global_load_lds_dwordx4 v[4:5], off
	v_lshl_add_u64 v[4:5], v[6:7], 0, s[8:9]
	s_mov_b32 m0, s33
	s_addc_u32 s1, s41, 0
	global_load_lds_dwordx4 v[4:5], off
	s_add_i32 m0, s48, 0x1c000
	v_lshl_add_u64 v[4:5], s[0:1], 0, v[152:153]
	global_load_lds_dwordx4 v[4:5], off
	v_lshl_add_u64 v[4:5], s[0:1], 0, v[156:157]
	s_add_i32 m0, s48, 0x1e000
	s_movk_i32 s0, 0x3c0
	global_load_lds_dwordx4 v[4:5], off
	s_waitcnt vmcnt(8)
	s_barrier
	v_and_b32_e32 v4, 48, v12
	v_lshlrev_b32_e32 v5, 6, v12
	v_and_or_b32 v4, v5, s0, v4
	v_lshlrev_b32_e32 v5, 2, v12
	v_and_b32_e32 v5, 32, v5
	v_bitop3_b32 v6, v4, s4, v5 bitop3:0xde
	v_bitop3_b32 v185, s5, v4, v5 bitop3:0xf6
	v_add_u32_e32 v185, 0x10000, v185
	v_lshlrev_b32_e32 v4, 15, v2
	v_writelane_b32 v242, s24, 29
	v_and_b32_e32 v4, 0xffff0000, v4
	v_lshl_add_u32 v4, v13, 12, v4
	v_writelane_b32 v242, s25, 30
	v_and_b32_e32 v2, 1, v2
	v_writelane_b32 v242, s20, 31
	v_lshl_or_b32 v2, v2, 6, v4
	s_cmp_gt_i32 s56, 63
	v_writelane_b32 v242, s21, 32
	v_lshl_add_u32 v158, v14, 1, v2
	v_lshlrev_b32_e32 v2, 15, v15
	v_writelane_b32 v242, s18, 35
	s_cselect_b64 s[84:85], -1, 0
	s_add_i32 s88, s31, -2
	v_and_b32_e32 v2, 0xffff0000, v2
	v_writelane_b32 v242, s19, 36
	s_cmpk_lt_u32 s58, 0x100
	v_lshl_add_u32 v2, v16, 12, v2
	v_and_b32_e32 v4, 1, v15
	v_writelane_b32 v242, s16, 37
	s_waitcnt vmcnt(6)
	s_cselect_b64 s[56:57], -1, 0
	s_and_b32 s0, s58, 0xffffff00
	v_lshl_or_b32 v2, v4, 6, v2
	v_mov_b32_e32 v4, v3
	v_mov_b32_e32 v5, v3
	v_writelane_b32 v242, s17, 38
	v_and_b32_e32 v184, 63, v12
	s_add_i32 s89, s0, 0
	v_lshl_add_u32 v160, v17, 1, v2
	v_mov_b32_e32 v2, v3
	v_add_u32_e32 v186, 0, v6
	v_mov_b64_e32 v[8:9], v[4:5]
	v_mov_b64_e32 v[12:13], v[4:5]
	v_mov_b64_e32 v[16:17], v[4:5]
	v_mov_b64_e32 v[20:21], v[4:5]
	v_mov_b64_e32 v[24:25], v[4:5]
	v_mov_b64_e32 v[28:29], v[4:5]
	v_mov_b64_e32 v[32:33], v[4:5]
	v_mov_b64_e32 v[36:37], v[4:5]
	v_mov_b64_e32 v[40:41], v[4:5]
	v_mov_b64_e32 v[44:45], v[4:5]
	v_mov_b64_e32 v[48:49], v[4:5]
	v_mov_b64_e32 v[52:53], v[4:5]
	v_mov_b64_e32 v[56:57], v[4:5]
	v_mov_b64_e32 v[60:61], v[4:5]
	v_mov_b64_e32 v[64:65], v[4:5]
	v_mov_b64_e32 v[68:69], v[4:5]
	v_mov_b64_e32 v[72:73], v[4:5]
	v_mov_b64_e32 v[76:77], v[4:5]
	v_mov_b64_e32 v[80:81], v[4:5]
	v_mov_b64_e32 v[84:85], v[4:5]
	v_mov_b64_e32 v[88:89], v[4:5]
	v_mov_b64_e32 v[92:93], v[4:5]
	v_mov_b64_e32 v[96:97], v[4:5]
	v_mov_b64_e32 v[100:101], v[4:5]
	v_mov_b64_e32 v[104:105], v[4:5]
	v_mov_b64_e32 v[108:109], v[4:5]
	v_mov_b64_e32 v[112:113], v[4:5]
	v_mov_b64_e32 v[116:117], v[4:5]
	v_mov_b64_e32 v[120:121], v[4:5]
	v_mov_b64_e32 v[124:125], v[4:5]
	v_mov_b64_e32 v[128:129], v[4:5]
	v_mov_b64_e32 v[132:133], v[4:5]
	v_writelane_b32 v242, s6, 33
	s_add_i32 s89, s89, 0x20000
	v_mov_b32_e32 v159, v3
	v_mov_b32_e32 v161, v3
	s_mov_b32 s92, 0
	v_mov_b64_e32 v[6:7], v[2:3]
	v_mov_b64_e32 v[10:11], v[2:3]
	v_mov_b64_e32 v[14:15], v[2:3]
	v_mov_b64_e32 v[18:19], v[2:3]
	v_mov_b64_e32 v[22:23], v[2:3]
	v_mov_b64_e32 v[26:27], v[2:3]
	v_mov_b64_e32 v[30:31], v[2:3]
	v_mov_b64_e32 v[34:35], v[2:3]
	v_mov_b64_e32 v[38:39], v[2:3]
	v_mov_b64_e32 v[42:43], v[2:3]
	v_mov_b64_e32 v[46:47], v[2:3]
	v_mov_b64_e32 v[50:51], v[2:3]
	v_mov_b64_e32 v[54:55], v[2:3]
	v_mov_b64_e32 v[58:59], v[2:3]
	v_mov_b64_e32 v[62:63], v[2:3]
	v_mov_b64_e32 v[66:67], v[2:3]
	v_mov_b64_e32 v[70:71], v[2:3]
	v_mov_b64_e32 v[74:75], v[2:3]
	v_mov_b64_e32 v[78:79], v[2:3]
	v_mov_b64_e32 v[82:83], v[2:3]
	v_mov_b64_e32 v[86:87], v[2:3]
	v_mov_b64_e32 v[90:91], v[2:3]
	v_mov_b64_e32 v[94:95], v[2:3]
	v_mov_b64_e32 v[98:99], v[2:3]
	v_mov_b64_e32 v[102:103], v[2:3]
	v_mov_b64_e32 v[106:107], v[2:3]
	v_mov_b64_e32 v[110:111], v[2:3]
	v_mov_b64_e32 v[114:115], v[2:3]
	v_mov_b64_e32 v[118:119], v[2:3]
	v_mov_b64_e32 v[122:123], v[2:3]
	v_mov_b64_e32 v[126:127], v[2:3]
	v_mov_b64_e32 v[130:131], v[2:3]
	v_writelane_b32 v242, s7, 34
	s_barrier
	s_branch .LBB0_949

; #define PG8_STAGE(bufoff, gbase, voff) do { _Pragma("unroll") for (int _i = 0; _i < 2; ++_i) \
;         __builtin_amdgcn_global_load_lds((const unsigned*)((const char*)(gbase) + (voff)[_i]), (LAS unsigned*)(lds + (bufoff) + ldsw + _i * 8192), 16, 0, 0); } while (0)
; #define PG8_WAIT_V(n) asm volatile("s_waitcnt vmcnt(" #n ")" ::: "memory")
; #define PG8_BAR __builtin_amdgcn_s_barrier()
; template <class Epi, bool ALIGN_EPI = true>
; __device__ __forceinline__ void gemm_phase(LAS unsigned char* lds, const Gemm g, const Sched& S, const Epi& E) {
;     ...
;     for (int i = 0; i < 2; ++i) { int R, C; stage_rc(tid * 16 + i * 8192, R, C); const int Rb = (R & ~31) + perm32(R & 31);
;         voffA[i] = (unsigned)(R * g.lda + C) * 2u; voffB[i] = (unsigned)(Rb * g.ldb + C) * 2u; }
;     const size_t kstep = (size_t)(BK * 2);
;     const size_t hstepA = (size_t)HALF * g.lda * 2, hstepB = (size_t)HALF * g.ldb * 2;
;     const unsigned ldsw = (unsigned)wid * 1024u;
;     const int aoff = lds_byte(wr * 64 + fr, fq * 8), boff = lds_byte(wc * 32 + fr, fq * 8);
;     ...
;     PG8_STAGE(PG8_SB(0, 0), cB, voffB); PG8_STAGE(PG8_SB(0, 1), cB + hstepB, voffB); PG8_STAGE(PG8_SA(0, 0), cA, voffA); PG8_STAGE(PG8_SA(0, 1), cA + hstepA, voffA);
;     if (wr == 1) PG8_BAR;
;     PG8_WAIT_V(2); PG8_BAR;
;     PG8_STAGE(PG8_SB(1, 0), cB + kstep, voffB); PG8_STAGE(PG8_SA(1, 0), cA + kstep, voffA); PG8_STAGE(PG8_SB(1, 1), cB + hstepB + kstep, voffB);
;     PG8_WAIT_V(6); PG8_BAR;
.LBB0_1220:
	v_readlane_b32 s20, v246, 42
	v_readlane_b32 s22, v246, 44
	v_readlane_b32 s23, v246, 45
	s_add_u32 s78, s22, s4
	s_addc_u32 s79, s23, s5
	s_add_u32 s4, s22, s14
	s_addc_u32 s5, s23, s15
	s_add_u32 s6, s22, s6
	s_addc_u32 s7, s23, s7
	s_ashr_i32 s14, s17, 31
	v_and_b32_e32 v223, 63, v2
	s_lshr_b32 s14, s14, 26
	v_and_b32_e32 v12, 48, v2
	v_lshlrev_b32_e32 v13, 6, v2
	s_movk_i32 s10, 0x3c0
	v_lshlrev_b32_e32 v2, 2, v2
	s_and_b32 s19, s19, 3
	s_add_i32 s17, s17, s14
	s_lshl_b32 s14, s18, 13
	v_and_or_b32 v12, v13, s10, v12
	v_and_b32_e32 v2, 32, v2
	s_add_i32 m0, s36, 0x18000
	v_lshl_add_u64 v[10:11], v[10:11], 0, s[8:9]
	s_ashr_i32 s85, s17, 6
	s_lshl_b32 s80, s18, 6
	v_bitop3_b32 v13, v12, s14, v2 bitop3:0xde
	s_lshl_b32 s14, s19, 12
	global_load_lds_dwordx4 v[10:11], off
	v_lshl_add_u64 v[8:9], v[8:9], 0, s[8:9]
	s_add_i32 m0, s36, 0x1a000
	s_add_i32 s81, s36, 0x8000
	s_add_i32 s82, s36, 0xa000
	v_bitop3_b32 v224, v12, s14, v2 bitop3:0xde
	v_add_u32_e32 v224, 0x10000, v224
	global_load_lds_dwordx4 v[8:9], off
	v_lshl_add_u64 v[4:5], v[4:5], 0, s[8:9]
	s_mov_b32 m0, s81
	s_add_u32 s14, s54, 0x80080
	global_load_lds_dwordx4 v[4:5], off
	v_lshl_add_u64 v[4:5], v[6:7], 0, s[8:9]
	s_mov_b32 m0, s82
	s_addc_u32 s15, s55, 0
	global_load_lds_dwordx4 v[4:5], off
	s_add_i32 m0, s36, 0x1c000
	v_lshl_add_u64 v[4:5], s[14:15], 0, v[206:207]
	global_load_lds_dwordx4 v[4:5], off
	v_lshl_add_u64 v[4:5], s[14:15], 0, v[194:195]
	s_add_i32 m0, s36, 0x1e000
	s_lshl_b32 s83, s19, 6
	global_load_lds_dwordx4 v[4:5], off
	s_waitcnt vmcnt(8)
	s_barrier
	s_ashr_i32 s84, s17, 7
	s_add_i32 s85, s85, -2
	v_readlane_b32 s18, v243, 43
	s_waitcnt vmcnt(6)
	s_cmpk_lt_u32 s16, 0x100
	v_readlane_b32 s19, v243, 44
	s_cselect_b64 s[14:15], -1, 0
	s_cmp_gt_i32 s84, 0
	s_mov_b32 s48, s18
	v_readlane_b32 s18, v243, 39
	s_mov_b32 s86, 0
	s_cselect_b64 s[16:17], -1, 0
	v_add_u32_e32 v225, 0, v13
	s_mov_b32 s49, s18
	v_readlane_b32 s21, v246, 43
	s_barrier
	v_readlane_b32 s19, v243, 40
	s_branch .LBB0_1223

; #define LAS __attribute__((address_space(3)))
; #define PG8_WAIT_V(n) asm volatile("s_waitcnt vmcnt(" #n ")" ::: "memory")
; #define PG8_BAR __builtin_amdgcn_s_barrier()
; template <class Epi, bool ALIGN_EPI = true>
; __device__ __forceinline__ void gemm_phase(LAS unsigned char* lds, const Gemm g, const Sched& S, const Epi& E) {
;     ...
;     for (int i = 0; i < 2; ++i) { int R, C; stage_rc(tid * 16 + i * 8192, R, C); const int Rb = (R & ~31) + perm32(R & 31);
;         voffA[i] = (unsigned)(R * g.lda + C) * 2u; voffB[i] = (unsigned)(Rb * g.ldb + C) * 2u; }
;     const size_t kstep = (size_t)(BK * 2);
;     const size_t hstepA = (size_t)HALF * g.lda * 2, hstepB = (size_t)HALF * g.ldb * 2;
;     const unsigned ldsw = (unsigned)wid * 1024u;
;     const int aoff = lds_byte(wr * 64 + fr, fq * 8), boff = lds_byte(wc * 32 + fr, fq * 8);
;     ...
;     Unit cur, nxt; int ui = 0;
;     if (!S.next(0, cur)) return;
;     if constexpr (Epi::USES_RSTD) {
;         LAS float* T = (LAS float*)(lds + RSTD_OFF);
; #pragma unroll
;         for (int k = 0; k < RSTD_UNITS * 256 / 512; ++k) { const int idx = tid + 512 * k; Unit uu;
;             if (S.next(idx >> 8, uu)) { const float* sp = E.SS + uu.pm * BM + (idx & 255); float ssum = 0.f;
; #pragma unroll
;                 for (int j = 0; j < 8; ++j) ssum += sp[(size_t)j * MROWS];
;                 T[idx] = __builtin_amdgcn_rsqf(ssum * (1.0f / DM) + EPS); } }
;         asm volatile("s_waitcnt lgkmcnt(0)" ::: "memory"); __builtin_amdgcn_s_barrier(); asm volatile("" ::: "memory");
;     }
;     f32x4 acc[2][2][4][2];
; #pragma unroll
;     for (int a = 0; a < 2; ++a)
; #pragma unroll
;         for (int b = 0; b < 2; ++b)
; #pragma unroll
;             for (int m = 0; m < 4; ++m)
; #pragma unroll
;                 for (int n = 0; n < 2; ++n) acc[a][b][m][n] = (f32x4){0.f, 0.f, 0.f, 0.f};
;     bf16x8 At[4][2], B0[2][2], B1[2][2];
;     const char* cA = (const char*)g.A + cur.aoff; const char* cB = (const char*)g.Bt + cur.boff;
;     PG8_STAGE(PG8_SB(0, 0), cB, voffB); PG8_STAGE(PG8_SB(0, 1), cB + hstepB, voffB); PG8_STAGE(PG8_SA(0, 0), cA, voffA); PG8_STAGE(PG8_SA(0, 1), cA + hstepA, voffA);
;     if (wr == 1) PG8_BAR;
;     PG8_WAIT_V(2); PG8_BAR;
;     PG8_STAGE(PG8_SB(1, 0), cB + kstep, voffB); PG8_STAGE(PG8_SA(1, 0), cA + kstep, voffA); PG8_STAGE(PG8_SB(1, 1), cB + hstepB + kstep, voffB);
;     PG8_WAIT_V(6); PG8_BAR;
.LBB0_1300:
	s_ashr_i32 s19, s18, 31
	s_lshr_b32 s19, s19, 26
	s_and_b32 s5, s5, 3
	s_add_i32 s19, s18, s19
	s_add_i32 m0, s52, 0x18000
	v_lshl_add_u64 v[10:11], v[10:11], 0, s[8:9]
	s_ashr_i32 s56, s19, 6
	s_lshl_b32 s31, s4, 6
	s_lshl_b32 s4, s4, 13
	s_lshl_b32 s19, s5, 12
	global_load_lds_dwordx4 v[10:11], off
	v_lshl_add_u64 v[8:9], v[8:9], 0, s[8:9]
	s_add_i32 m0, s52, 0x1a000
	s_add_i32 s57, s52, 0x8000
	s_add_i32 s58, s52, 0xa000
	global_load_lds_dwordx4 v[8:9], off
	v_lshl_add_u64 v[6:7], v[6:7], 0, s[8:9]
	s_mov_b32 m0, s57
	s_add_u32 s20, s14, 0x80080
	global_load_lds_dwordx4 v[6:7], off
	v_lshl_add_u64 v[4:5], v[4:5], 0, s[8:9]
	s_mov_b32 m0, s58
	s_addc_u32 s21, s15, 0
	global_load_lds_dwordx4 v[4:5], off
	s_add_i32 m0, s52, 0x1c000
	v_lshl_add_u64 v[4:5], s[20:21], 0, v[138:139]
	global_load_lds_dwordx4 v[4:5], off
	v_lshl_add_u64 v[4:5], s[20:21], 0, v[134:135]
	s_add_i32 m0, s52, 0x1e000
	s_movk_i32 s10, 0x3c0
	global_load_lds_dwordx4 v[4:5], off
	s_waitcnt vmcnt(8)
	s_barrier
	v_and_b32_e32 v4, 48, v146
	v_lshlrev_b32_e32 v5, 6, v146
	v_and_or_b32 v4, v5, s10, v4
	v_lshlrev_b32_e32 v5, 2, v146
	v_and_b32_e32 v5, 32, v5
	v_bitop3_b32 v6, v4, s4, v5 bitop3:0xde
	v_bitop3_b32 v147, v4, s19, v5 bitop3:0xde
	v_add_u32_e32 v147, 0x10000, v147
	v_lshlrev_b32_e32 v4, 15, v15
	v_and_b32_e32 v4, 0xffff0000, v4
	v_lshl_add_u32 v4, v14, 12, v4
	v_and_b32_e32 v5, 1, v15
	v_lshl_or_b32 v4, v5, 6, v4
	v_lshl_add_u32 v142, v16, 1, v4
	v_lshlrev_b32_e32 v4, 15, v2
	v_and_b32_e32 v4, 0xffff0000, v4
	v_lshl_add_u32 v4, v12, 12, v4
	v_and_b32_e32 v2, 1, v2
	v_readlane_b32 s20, v243, 43
	s_waitcnt vmcnt(6)
	v_lshl_or_b32 v2, v2, 6, v4
	v_mov_b32_e32 v4, v3
	v_mov_b32_e32 v5, v3
	v_readlane_b32 s21, v243, 44
	s_cmp_gt_i32 s18, 63
	v_lshl_add_u32 v144, v13, 1, v2
	v_mov_b32_e32 v2, v3
	v_add_u32_e32 v148, 0, v6
	v_mov_b64_e32 v[8:9], v[4:5]
	v_mov_b64_e32 v[12:13], v[4:5]
	v_mov_b64_e32 v[24:25], v[4:5]
	v_mov_b64_e32 v[28:29], v[4:5]
	v_mov_b64_e32 v[40:41], v[4:5]
	v_mov_b64_e32 v[44:45], v[4:5]
	v_mov_b64_e32 v[56:57], v[4:5]
	v_mov_b64_e32 v[60:61], v[4:5]
	v_mov_b64_e32 v[16:17], v[4:5]
	v_mov_b64_e32 v[20:21], v[4:5]
	v_mov_b64_e32 v[32:33], v[4:5]
	v_mov_b64_e32 v[36:37], v[4:5]
	v_mov_b64_e32 v[48:49], v[4:5]
	v_mov_b64_e32 v[52:53], v[4:5]
	v_mov_b64_e32 v[64:65], v[4:5]
	v_mov_b64_e32 v[68:69], v[4:5]
	v_mov_b64_e32 v[72:73], v[4:5]
	v_mov_b64_e32 v[76:77], v[4:5]
	v_mov_b64_e32 v[88:89], v[4:5]
	v_mov_b64_e32 v[92:93], v[4:5]
	v_mov_b64_e32 v[104:105], v[4:5]
	v_mov_b64_e32 v[108:109], v[4:5]
	v_mov_b64_e32 v[120:121], v[4:5]
	v_mov_b64_e32 v[124:125], v[4:5]
	v_mov_b64_e32 v[80:81], v[4:5]
	v_mov_b64_e32 v[84:85], v[4:5]
	v_mov_b64_e32 v[96:97], v[4:5]
	v_mov_b64_e32 v[100:101], v[4:5]
	v_mov_b64_e32 v[112:113], v[4:5]
	v_mov_b64_e32 v[116:117], v[4:5]
	v_mov_b64_e32 v[128:129], v[4:5]
	v_mov_b64_e32 v[132:133], v[4:5]
	s_mov_b32 s4, s20
	v_readlane_b32 s20, v243, 39
	s_cselect_b64 s[18:19], -1, 0
	s_add_i32 s59, s56, -2
	v_mov_b32_e32 v143, v3
	v_mov_b32_e32 v145, v3
	s_mov_b32 s60, 0
	v_mov_b64_e32 v[6:7], v[2:3]
	v_mov_b64_e32 v[10:11], v[2:3]
	v_mov_b64_e32 v[22:23], v[2:3]
	v_mov_b64_e32 v[26:27], v[2:3]
	v_mov_b64_e32 v[38:39], v[2:3]
	v_mov_b64_e32 v[42:43], v[2:3]
	v_mov_b64_e32 v[54:55], v[2:3]
	v_mov_b64_e32 v[58:59], v[2:3]
	v_mov_b64_e32 v[14:15], v[2:3]
	v_mov_b64_e32 v[18:19], v[2:3]
	v_mov_b64_e32 v[30:31], v[2:3]
	v_mov_b64_e32 v[34:35], v[2:3]
	v_mov_b64_e32 v[46:47], v[2:3]
	v_mov_b64_e32 v[50:51], v[2:3]
	v_mov_b64_e32 v[62:63], v[2:3]
	v_mov_b64_e32 v[66:67], v[2:3]
	v_mov_b64_e32 v[70:71], v[2:3]
	v_mov_b64_e32 v[74:75], v[2:3]
	v_mov_b64_e32 v[86:87], v[2:3]
	v_mov_b64_e32 v[90:91], v[2:3]
	v_mov_b64_e32 v[102:103], v[2:3]
	v_mov_b64_e32 v[106:107], v[2:3]
	v_mov_b64_e32 v[118:119], v[2:3]
	v_mov_b64_e32 v[122:123], v[2:3]
	v_mov_b64_e32 v[78:79], v[2:3]
	v_mov_b64_e32 v[82:83], v[2:3]
	v_mov_b64_e32 v[94:95], v[2:3]
	v_mov_b64_e32 v[98:99], v[2:3]
	v_mov_b64_e32 v[110:111], v[2:3]
	v_mov_b64_e32 v[114:115], v[2:3]
	v_mov_b64_e32 v[126:127], v[2:3]
	v_mov_b64_e32 v[130:131], v[2:3]
	s_mov_b32 s61, s20
	s_barrier
	v_readlane_b32 s21, v243, 40
	s_branch .LBB0_1302

; #define LAS __attribute__((address_space(3)))
; #define PG8_WAIT_V(n) asm volatile("s_waitcnt vmcnt(" #n ")" ::: "memory")
; #define PG8_BAR __builtin_amdgcn_s_barrier()
; template <class Epi, bool ALIGN_EPI = true>
; __device__ __forceinline__ void gemm_phase(LAS unsigned char* lds, const Gemm g, const Sched& S, const Epi& E) {
;     ...
;     for (int i = 0; i < 2; ++i) { int R, C; stage_rc(tid * 16 + i * 8192, R, C); const int Rb = (R & ~31) + perm32(R & 31);
;         voffA[i] = (unsigned)(R * g.lda + C) * 2u; voffB[i] = (unsigned)(Rb * g.ldb + C) * 2u; }
;     const size_t kstep = (size_t)(BK * 2);
;     const size_t hstepA = (size_t)HALF * g.lda * 2, hstepB = (size_t)HALF * g.ldb * 2;
;     const unsigned ldsw = (unsigned)wid * 1024u;
;     const int aoff = lds_byte(wr * 64 + fr, fq * 8), boff = lds_byte(wc * 32 + fr, fq * 8);
;     ...
;     Unit cur, nxt; int ui = 0;
;     if (!S.next(0, cur)) return;
;     if constexpr (Epi::USES_RSTD) {
;         LAS float* T = (LAS float*)(lds + RSTD_OFF);
; #pragma unroll
;         for (int k = 0; k < RSTD_UNITS * 256 / 512; ++k) { const int idx = tid + 512 * k; Unit uu;
;             if (S.next(idx >> 8, uu)) { const float* sp = E.SS + uu.pm * BM + (idx & 255); float ssum = 0.f;
; #pragma unroll
;                 for (int j = 0; j < 8; ++j) ssum += sp[(size_t)j * MROWS];
;                 T[idx] = __builtin_amdgcn_rsqf(ssum * (1.0f / DM) + EPS); } }
;         asm volatile("s_waitcnt lgkmcnt(0)" ::: "memory"); __builtin_amdgcn_s_barrier(); asm volatile("" ::: "memory");
;     }
;     f32x4 acc[2][2][4][2];
; #pragma unroll
;     for (int a = 0; a < 2; ++a)
; #pragma unroll
;         for (int b = 0; b < 2; ++b)
; #pragma unroll
;             for (int m = 0; m < 4; ++m)
; #pragma unroll
;                 for (int n = 0; n < 2; ++n) acc[a][b][m][n] = (f32x4){0.f, 0.f, 0.f, 0.f};
;     bf16x8 At[4][2], B0[2][2], B1[2][2];
;     const char* cA = (const char*)g.A + cur.aoff; const char* cB = (const char*)g.Bt + cur.boff;
;     PG8_STAGE(PG8_SB(0, 0), cB, voffB); PG8_STAGE(PG8_SB(0, 1), cB + hstepB, voffB); PG8_STAGE(PG8_SA(0, 0), cA, voffA); PG8_STAGE(PG8_SA(0, 1), cA + hstepA, voffA);
;     if (wr == 1) PG8_BAR;
;     PG8_WAIT_V(2); PG8_BAR;
;     PG8_STAGE(PG8_SB(1, 0), cB + kstep, voffB); PG8_STAGE(PG8_SA(1, 0), cA + kstep, voffA); PG8_STAGE(PG8_SB(1, 1), cB + hstepB + kstep, voffB);
;     PG8_WAIT_V(6); PG8_BAR;
.LBB0_1391:
	s_and_b32 s30, s18, 3
	s_ashr_i32 s18, s16, 31
	s_lshr_b32 s18, s18, 26
	s_add_i32 s18, s16, s18
	s_add_i32 m0, s52, 0x18000
	v_lshl_add_u64 v[10:11], v[10:11], 0, s[8:9]
	s_ashr_i32 s56, s18, 6
	s_lshl_b32 s33, s17, 6
	s_lshl_b32 s17, s17, 13
	s_lshl_b32 s20, s30, 12
	global_load_lds_dwordx4 v[10:11], off
	v_lshl_add_u64 v[8:9], v[8:9], 0, s[8:9]
	s_add_i32 m0, s52, 0x1a000
	s_add_i32 s57, s52, 0x8000
	s_add_i32 s58, s52, 0xa000
	global_load_lds_dwordx4 v[8:9], off
	v_lshl_add_u64 v[6:7], v[6:7], 0, s[8:9]
	s_mov_b32 m0, s57
	s_add_u32 s18, s6, 0x80080
	global_load_lds_dwordx4 v[6:7], off
	v_lshl_add_u64 v[4:5], v[4:5], 0, s[8:9]
	s_mov_b32 m0, s58
	s_addc_u32 s19, s7, 0
	global_load_lds_dwordx4 v[4:5], off
	s_add_i32 m0, s52, 0x1c000
	v_lshl_add_u64 v[4:5], s[18:19], 0, v[138:139]
	global_load_lds_dwordx4 v[4:5], off
	v_lshl_add_u64 v[4:5], s[18:19], 0, v[134:135]
	s_add_i32 m0, s52, 0x1e000
	s_movk_i32 s10, 0x3c0
	global_load_lds_dwordx4 v[4:5], off
	s_waitcnt vmcnt(8)
	s_barrier
	v_and_b32_e32 v4, 48, v146
	v_lshlrev_b32_e32 v5, 6, v146
	v_and_or_b32 v4, v5, s10, v4
	v_lshlrev_b32_e32 v5, 2, v146
	v_and_b32_e32 v5, 32, v5
	v_bitop3_b32 v6, v4, s17, v5 bitop3:0xde
	v_bitop3_b32 v147, v4, s20, v5 bitop3:0xde
	v_add_u32_e32 v147, 0x10000, v147
	v_lshlrev_b32_e32 v4, 15, v15
	v_and_b32_e32 v4, 0xffff0000, v4
	v_lshl_add_u32 v4, v14, 12, v4
	v_and_b32_e32 v5, 1, v15
	v_lshl_or_b32 v4, v5, 6, v4
	v_lshl_add_u32 v142, v16, 1, v4
	v_lshlrev_b32_e32 v4, 15, v2
	v_and_b32_e32 v4, 0xffff0000, v4
	v_lshl_add_u32 v4, v12, 12, v4
	v_and_b32_e32 v2, 1, v2
	v_readlane_b32 s18, v243, 16
	s_waitcnt vmcnt(6)
	v_lshl_or_b32 v2, v2, 6, v4
	v_mov_b32_e32 v4, v3
	v_mov_b32_e32 v5, v3
	v_readlane_b32 s19, v243, 17
	s_cmp_gt_i32 s16, 63
	v_lshl_add_u32 v144, v13, 1, v2
	v_mov_b32_e32 v2, v3
	v_add_u32_e32 v148, 0, v6
	v_mov_b64_e32 v[8:9], v[4:5]
	v_mov_b64_e32 v[12:13], v[4:5]
	v_mov_b64_e32 v[24:25], v[4:5]
	v_mov_b64_e32 v[28:29], v[4:5]
	v_mov_b64_e32 v[40:41], v[4:5]
	v_mov_b64_e32 v[44:45], v[4:5]
	v_mov_b64_e32 v[56:57], v[4:5]
	v_mov_b64_e32 v[60:61], v[4:5]
	v_mov_b64_e32 v[16:17], v[4:5]
	v_mov_b64_e32 v[20:21], v[4:5]
	v_mov_b64_e32 v[32:33], v[4:5]
	v_mov_b64_e32 v[36:37], v[4:5]
	v_mov_b64_e32 v[48:49], v[4:5]
	v_mov_b64_e32 v[52:53], v[4:5]
	v_mov_b64_e32 v[64:65], v[4:5]
	v_mov_b64_e32 v[68:69], v[4:5]
	v_mov_b64_e32 v[72:73], v[4:5]
	v_mov_b64_e32 v[76:77], v[4:5]
	v_mov_b64_e32 v[88:89], v[4:5]
	v_mov_b64_e32 v[92:93], v[4:5]
	v_mov_b64_e32 v[104:105], v[4:5]
	v_mov_b64_e32 v[108:109], v[4:5]
	v_mov_b64_e32 v[120:121], v[4:5]
	v_mov_b64_e32 v[124:125], v[4:5]
	v_mov_b64_e32 v[80:81], v[4:5]
	v_mov_b64_e32 v[84:85], v[4:5]
	v_mov_b64_e32 v[96:97], v[4:5]
	v_mov_b64_e32 v[100:101], v[4:5]
	v_mov_b64_e32 v[112:113], v[4:5]
	v_mov_b64_e32 v[116:117], v[4:5]
	v_mov_b64_e32 v[128:129], v[4:5]
	v_mov_b64_e32 v[132:133], v[4:5]
	s_mov_b32 s31, s18
	v_readlane_b32 s18, v243, 12
	s_cselect_b64 s[16:17], -1, 0
	s_add_i32 s59, s56, -2
	v_mov_b32_e32 v143, v3
	v_mov_b32_e32 v145, v3
	s_mov_b32 s60, 0
	v_mov_b64_e32 v[6:7], v[2:3]
	v_mov_b64_e32 v[10:11], v[2:3]
	v_mov_b64_e32 v[22:23], v[2:3]
	v_mov_b64_e32 v[26:27], v[2:3]
	v_mov_b64_e32 v[38:39], v[2:3]
	v_mov_b64_e32 v[42:43], v[2:3]
	v_mov_b64_e32 v[54:55], v[2:3]
	v_mov_b64_e32 v[58:59], v[2:3]
	v_mov_b64_e32 v[14:15], v[2:3]
	v_mov_b64_e32 v[18:19], v[2:3]
	v_mov_b64_e32 v[30:31], v[2:3]
	v_mov_b64_e32 v[34:35], v[2:3]
	v_mov_b64_e32 v[46:47], v[2:3]
	v_mov_b64_e32 v[50:51], v[2:3]
	v_mov_b64_e32 v[62:63], v[2:3]
	v_mov_b64_e32 v[66:67], v[2:3]
	v_mov_b64_e32 v[70:71], v[2:3]
	v_mov_b64_e32 v[74:75], v[2:3]
	v_mov_b64_e32 v[86:87], v[2:3]
	v_mov_b64_e32 v[90:91], v[2:3]
	v_mov_b64_e32 v[102:103], v[2:3]
	v_mov_b64_e32 v[106:107], v[2:3]
	v_mov_b64_e32 v[118:119], v[2:3]
	v_mov_b64_e32 v[122:123], v[2:3]
	v_mov_b64_e32 v[78:79], v[2:3]
	v_mov_b64_e32 v[82:83], v[2:3]
	v_mov_b64_e32 v[94:95], v[2:3]
	v_mov_b64_e32 v[98:99], v[2:3]
	v_mov_b64_e32 v[110:111], v[2:3]
	v_mov_b64_e32 v[114:115], v[2:3]
	v_mov_b64_e32 v[126:127], v[2:3]
	v_mov_b64_e32 v[130:131], v[2:3]
	s_mov_b32 s61, s18
	s_barrier
	v_readlane_b32 s19, v243, 13
	s_branch .LBB0_1393

; #define PG8_STAGE(bufoff, gbase, voff) do { _Pragma("unroll") for (int _i = 0; _i < 2; ++_i) \
;         __builtin_amdgcn_global_load_lds((const unsigned*)((const char*)(gbase) + (voff)[_i]), (LAS unsigned*)(lds + (bufoff) + ldsw + _i * 8192), 16, 0, 0); } while (0)
; #define PG8_WAIT_V(n) asm volatile("s_waitcnt vmcnt(" #n ")" ::: "memory")
; #define PG8_BAR __builtin_amdgcn_s_barrier()
; template <class Epi, bool ALIGN_EPI = true>
; __device__ __forceinline__ void gemm_phase(LAS unsigned char* lds, const Gemm g, const Sched& S, const Epi& E) {
;     ...
;     for (int i = 0; i < 2; ++i) { int R, C; stage_rc(tid * 16 + i * 8192, R, C); const int Rb = (R & ~31) + perm32(R & 31);
;         voffA[i] = (unsigned)(R * g.lda + C) * 2u; voffB[i] = (unsigned)(Rb * g.ldb + C) * 2u; }
;     const size_t kstep = (size_t)(BK * 2);
;     const size_t hstepA = (size_t)HALF * g.lda * 2, hstepB = (size_t)HALF * g.ldb * 2;
;     const unsigned ldsw = (unsigned)wid * 1024u;
;     const int aoff = lds_byte(wr * 64 + fr, fq * 8), boff = lds_byte(wc * 32 + fr, fq * 8);
;     ...
;     PG8_STAGE(PG8_SB(0, 0), cB, voffB); PG8_STAGE(PG8_SB(0, 1), cB + hstepB, voffB); PG8_STAGE(PG8_SA(0, 0), cA, voffA); PG8_STAGE(PG8_SA(0, 1), cA + hstepA, voffA);
;     if (wr == 1) PG8_BAR;
;     PG8_WAIT_V(2); PG8_BAR;
;     PG8_STAGE(PG8_SB(1, 0), cB + kstep, voffB); PG8_STAGE(PG8_SA(1, 0), cA + kstep, voffA); PG8_STAGE(PG8_SB(1, 1), cB + hstepB + kstep, voffB);
;     PG8_WAIT_V(6); PG8_BAR;
.LBB0_1445:
	s_add_u32 s18, s18, s0
	s_addc_u32 s19, s19, s1
	s_add_u32 s52, s18, 0x41800000
	s_addc_u32 s53, s19, 0
	s_ashr_i32 s18, s14, 31
	s_lshr_b32 s18, s18, 26
	s_lshl_b32 s15, s15, 5
	s_add_i32 s18, s14, s18
	s_and_b32 s56, s15, 0x60
	s_add_i32 m0, s48, 0x18000
	v_lshl_add_u64 v[10:11], v[10:11], 0, s[8:9]
	s_ashr_i32 s54, s18, 6
	s_lshl_b32 s55, s17, 6
	s_lshl_b32 s17, s17, 13
	s_lshl_b32 s15, s56, 7
	global_load_lds_dwordx4 v[10:11], off
	v_lshl_add_u64 v[8:9], v[8:9], 0, s[8:9]
	s_add_i32 m0, s48, 0x1a000
	s_add_i32 s57, s48, 0x8000
	s_add_i32 s58, s48, 0xa000
	global_load_lds_dwordx4 v[8:9], off
	v_lshl_add_u64 v[4:5], v[4:5], 0, s[8:9]
	s_mov_b32 m0, s57
	s_add_u32 s18, s26, 0x80080
	global_load_lds_dwordx4 v[4:5], off
	v_lshl_add_u64 v[4:5], v[6:7], 0, s[8:9]
	s_mov_b32 m0, s58
	s_addc_u32 s19, s27, 0
	global_load_lds_dwordx4 v[4:5], off
	s_add_i32 m0, s48, 0x1c000
	v_lshl_add_u64 v[4:5], s[18:19], 0, v[2:3]
	global_load_lds_dwordx4 v[4:5], off
	v_lshl_add_u64 v[4:5], s[18:19], 0, v[132:133]
	s_add_i32 m0, s48, 0x1e000
	v_and_b32_e32 v142, 63, v17
	global_load_lds_dwordx4 v[4:5], off
	s_waitcnt vmcnt(8)
	s_barrier
	v_lshlrev_b32_e32 v4, 18, v16
	v_and_b32_e32 v4, 0xfff80000, v4
	v_lshl_add_u32 v4, v15, 15, v4
	v_and_b32_e32 v5, 1, v16
	v_lshl_or_b32 v4, v5, 6, v4
	v_and_b32_e32 v19, 48, v17
	v_lshlrev_b32_e32 v20, 6, v17
	s_movk_i32 s10, 0x3c0
	v_lshlrev_b32_e32 v17, 2, v17
	v_lshl_add_u32 v138, v18, 1, v4
	v_lshlrev_b32_e32 v4, 18, v12
	v_and_or_b32 v19, v20, s10, v19
	v_and_b32_e32 v17, 32, v17
	s_cmp_gt_i32 s14, 63
	v_and_b32_e32 v4, 0xfff80000, v4
	v_bitop3_b32 v143, s15, v19, v17 bitop3:0xf6
	s_waitcnt vmcnt(6)
	s_cselect_b64 s[14:15], -1, 0
	s_add_i32 s59, s54, -2
	v_lshl_add_u32 v4, v13, 15, v4
	v_and_b32_e32 v5, 1, v12
	v_bitop3_b32 v20, v19, s17, v17 bitop3:0xde
	s_cmpk_lt_u32 s16, 0x100
	v_lshl_or_b32 v4, v5, 6, v4
	v_readlane_b32 s18, v243, 31
	s_cselect_b64 s[16:17], -1, 0
	v_mov_b32_e32 v139, v3
	v_lshl_add_u32 v140, v14, 1, v4
	v_mov_b32_e32 v141, v3
	s_mov_b32 s47, 0
	v_add_u32_e32 v144, 0, v20
	s_mov_b32 s63, s18
	v_readlane_b32 s62, v243, 20
	s_barrier
	v_readlane_b32 s19, v243, 32
	s_branch .LBB0_1448

; #define PG8_STAGE(bufoff, gbase, voff) do { _Pragma("unroll") for (int _i = 0; _i < 2; ++_i) \
;         __builtin_amdgcn_global_load_lds((const unsigned*)((const char*)(gbase) + (voff)[_i]), (LAS unsigned*)(lds + (bufoff) + ldsw + _i * 8192), 16, 0, 0); } while (0)
; #define PG8_WAIT_V(n) asm volatile("s_waitcnt vmcnt(" #n ")" ::: "memory")
; #define PG8_BAR __builtin_amdgcn_s_barrier()
; template <class Epi, bool ALIGN_EPI = true>
; __device__ __forceinline__ void gemm_phase(LAS unsigned char* lds, const Gemm g, const Sched& S, const Epi& E) {
;     ...
;     for (int i = 0; i < 2; ++i) { int R, C; stage_rc(tid * 16 + i * 8192, R, C); const int Rb = (R & ~31) + perm32(R & 31);
;         voffA[i] = (unsigned)(R * g.lda + C) * 2u; voffB[i] = (unsigned)(Rb * g.ldb + C) * 2u; }
;     const size_t kstep = (size_t)(BK * 2);
;     const size_t hstepA = (size_t)HALF * g.lda * 2, hstepB = (size_t)HALF * g.ldb * 2;
;     const unsigned ldsw = (unsigned)wid * 1024u;
;     const int aoff = lds_byte(wr * 64 + fr, fq * 8), boff = lds_byte(wc * 32 + fr, fq * 8);
;     ...
;     PG8_STAGE(PG8_SB(0, 0), cB, voffB); PG8_STAGE(PG8_SB(0, 1), cB + hstepB, voffB); PG8_STAGE(PG8_SA(0, 0), cA, voffA); PG8_STAGE(PG8_SA(0, 1), cA + hstepA, voffA);
;     if (wr == 1) PG8_BAR;
;     PG8_WAIT_V(2); PG8_BAR;
;     PG8_STAGE(PG8_SB(1, 0), cB + kstep, voffB); PG8_STAGE(PG8_SA(1, 0), cA + kstep, voffA); PG8_STAGE(PG8_SB(1, 1), cB + hstepB + kstep, voffB);
;     PG8_WAIT_V(6); PG8_BAR;
.LBB0_1467:
	s_add_u32 s16, s16, s0
	s_addc_u32 s17, s17, s1
	s_add_u32 s50, s16, 0x45800000
	s_addc_u32 s51, s17, 0
	s_ashr_i32 s16, s15, 31
	s_lshr_b32 s16, s16, 26
	s_lshl_b32 s6, s6, 5
	v_and_b32_e32 v142, 63, v18
	s_add_i32 s16, s15, s16
	v_and_b32_e32 v19, 48, v18
	v_lshlrev_b32_e32 v20, 6, v18
	s_movk_i32 s10, 0x3c0
	v_lshlrev_b32_e32 v18, 2, v18
	s_and_b32 s54, s6, 0x60
	s_add_i32 m0, s46, 0x18000
	v_lshl_add_u64 v[10:11], v[10:11], 0, s[8:9]
	s_ashr_i32 s52, s16, 6
	s_lshl_b32 s53, s7, 6
	s_lshl_b32 s7, s7, 13
	v_and_or_b32 v19, v20, s10, v19
	v_and_b32_e32 v18, 32, v18
	s_lshl_b32 s6, s54, 7
	global_load_lds_dwordx4 v[10:11], off
	v_lshl_add_u64 v[8:9], v[8:9], 0, s[8:9]
	s_add_i32 m0, s46, 0x1a000
	s_add_i32 s55, s46, 0x8000
	s_add_i32 s56, s46, 0xa000
	v_bitop3_b32 v143, s6, v19, v18 bitop3:0xf6
	global_load_lds_dwordx4 v[8:9], off
	v_lshl_add_u64 v[4:5], v[4:5], 0, s[8:9]
	s_mov_b32 m0, s55
	s_add_u32 s6, s26, 0x400080
	v_bitop3_b32 v20, v19, s7, v18 bitop3:0xde
	global_load_lds_dwordx4 v[4:5], off
	v_lshl_add_u64 v[4:5], v[6:7], 0, s[8:9]
	s_mov_b32 m0, s56
	s_addc_u32 s7, s27, 0
	global_load_lds_dwordx4 v[4:5], off
	s_add_i32 m0, s46, 0x1c000
	v_lshl_add_u64 v[4:5], s[6:7], 0, v[2:3]
	global_load_lds_dwordx4 v[4:5], off
	v_lshl_add_u64 v[4:5], s[6:7], 0, v[132:133]
	s_add_i32 m0, s46, 0x1e000
	s_cmp_gt_i32 s15, 63
	global_load_lds_dwordx4 v[4:5], off
	s_waitcnt vmcnt(8)
	s_barrier
	v_lshlrev_b32_e32 v4, 15, v16
	v_and_b32_e32 v4, 0xffff0000, v4
	v_lshl_add_u32 v4, v15, 12, v4
	v_and_b32_e32 v5, 1, v16
	v_lshl_or_b32 v4, v5, 6, v4
	v_lshl_add_u32 v138, v17, 1, v4
	v_lshlrev_b32_e32 v4, 15, v12
	v_and_b32_e32 v4, 0xffff0000, v4
	v_readlane_b32 s16, v243, 35
	s_waitcnt vmcnt(6)
	s_cselect_b64 s[6:7], -1, 0
	s_add_i32 s57, s52, -2
	v_lshl_add_u32 v4, v13, 12, v4
	v_and_b32_e32 v5, 1, v12
	v_readlane_b32 s17, v243, 36
	s_cmpk_lt_u32 s14, 0x100
	v_lshl_or_b32 v4, v5, 6, v4
	s_mov_b32 s61, s16
	v_readlane_b32 s16, v243, 23
	s_cselect_b64 s[14:15], -1, 0
	v_mov_b32_e32 v139, v3
	v_lshl_add_u32 v140, v14, 1, v4
	v_mov_b32_e32 v141, v3
	s_mov_b32 s45, 0
	v_add_u32_e32 v144, 0, v20
	s_mov_b32 s60, s16
	s_barrier
	v_readlane_b32 s17, v243, 24
	s_branch .LBB0_1470

; #define LAS __attribute__((address_space(3)))
; #define PG8_WAIT_V(n) asm volatile("s_waitcnt vmcnt(" #n ")" ::: "memory")
; #define PG8_BAR __builtin_amdgcn_s_barrier()
; template <class Epi, bool ALIGN_EPI = true>
; __device__ __forceinline__ void gemm_phase(LAS unsigned char* lds, const Gemm g, const Sched& S, const Epi& E) {
;     ...
;     for (int i = 0; i < 2; ++i) { int R, C; stage_rc(tid * 16 + i * 8192, R, C); const int Rb = (R & ~31) + perm32(R & 31);
;         voffA[i] = (unsigned)(R * g.lda + C) * 2u; voffB[i] = (unsigned)(Rb * g.ldb + C) * 2u; }
;     const size_t kstep = (size_t)(BK * 2);
;     const size_t hstepA = (size_t)HALF * g.lda * 2, hstepB = (size_t)HALF * g.ldb * 2;
;     const unsigned ldsw = (unsigned)wid * 1024u;
;     const int aoff = lds_byte(wr * 64 + fr, fq * 8), boff = lds_byte(wc * 32 + fr, fq * 8);
;     ...
;     Unit cur, nxt; int ui = 0;
;     if (!S.next(0, cur)) return;
;     if constexpr (Epi::USES_RSTD) {
;         LAS float* T = (LAS float*)(lds + RSTD_OFF);
; #pragma unroll
;         for (int k = 0; k < RSTD_UNITS * 256 / 512; ++k) { const int idx = tid + 512 * k; Unit uu;
;             if (S.next(idx >> 8, uu)) { const float* sp = E.SS + uu.pm * BM + (idx & 255); float ssum = 0.f;
; #pragma unroll
;                 for (int j = 0; j < 8; ++j) ssum += sp[(size_t)j * MROWS];
;                 T[idx] = __builtin_amdgcn_rsqf(ssum * (1.0f / DM) + EPS); } }
;         asm volatile("s_waitcnt lgkmcnt(0)" ::: "memory"); __builtin_amdgcn_s_barrier(); asm volatile("" ::: "memory");
;     }
;     f32x4 acc[2][2][4][2];
; #pragma unroll
;     for (int a = 0; a < 2; ++a)
; #pragma unroll
;         for (int b = 0; b < 2; ++b)
; #pragma unroll
;             for (int m = 0; m < 4; ++m)
; #pragma unroll
;                 for (int n = 0; n < 2; ++n) acc[a][b][m][n] = (f32x4){0.f, 0.f, 0.f, 0.f};
;     bf16x8 At[4][2], B0[2][2], B1[2][2];
;     const char* cA = (const char*)g.A + cur.aoff; const char* cB = (const char*)g.Bt + cur.boff;
;     PG8_STAGE(PG8_SB(0, 0), cB, voffB); PG8_STAGE(PG8_SB(0, 1), cB + hstepB, voffB); PG8_STAGE(PG8_SA(0, 0), cA, voffA); PG8_STAGE(PG8_SA(0, 1), cA + hstepA, voffA);
;     if (wr == 1) PG8_BAR;
;     PG8_WAIT_V(2); PG8_BAR;
;     PG8_STAGE(PG8_SB(1, 0), cB + kstep, voffB); PG8_STAGE(PG8_SA(1, 0), cA + kstep, voffA); PG8_STAGE(PG8_SB(1, 1), cB + hstepB + kstep, voffB);
;     PG8_WAIT_V(6); PG8_BAR;
.LBB0_1918:
	s_ashr_i32 s19, s18, 31
	s_lshr_b32 s19, s19, 26
	s_and_b32 s5, s5, 3
	s_add_i32 s19, s18, s19
	s_add_i32 m0, s52, 0x18000
	v_lshl_add_u64 v[10:11], v[10:11], 0, s[8:9]
	s_ashr_i32 s56, s19, 6
	s_lshl_b32 s31, s4, 6
	s_lshl_b32 s4, s4, 13
	s_lshl_b32 s19, s5, 12
	global_load_lds_dwordx4 v[10:11], off
	v_lshl_add_u64 v[8:9], v[8:9], 0, s[8:9]
	s_add_i32 m0, s52, 0x1a000
	s_add_i32 s57, s52, 0x8000
	s_add_i32 s58, s52, 0xa000
	global_load_lds_dwordx4 v[8:9], off
	v_lshl_add_u64 v[6:7], v[6:7], 0, s[8:9]
	s_mov_b32 m0, s57
	s_add_u32 s20, s14, 0x40080
	global_load_lds_dwordx4 v[6:7], off
	v_lshl_add_u64 v[4:5], v[4:5], 0, s[8:9]
	s_mov_b32 m0, s58
	s_addc_u32 s21, s15, 0
	global_load_lds_dwordx4 v[4:5], off
	s_add_i32 m0, s52, 0x1c000
	v_lshl_add_u64 v[4:5], s[20:21], 0, v[138:139]
	global_load_lds_dwordx4 v[4:5], off
	v_lshl_add_u64 v[4:5], s[20:21], 0, v[134:135]
	s_add_i32 m0, s52, 0x1e000
	s_movk_i32 s10, 0x3c0
	global_load_lds_dwordx4 v[4:5], off
	s_waitcnt vmcnt(8)
	s_barrier
	v_and_b32_e32 v4, 48, v146
	v_lshlrev_b32_e32 v5, 6, v146
	v_and_or_b32 v4, v5, s10, v4
	v_lshlrev_b32_e32 v5, 2, v146
	v_and_b32_e32 v5, 32, v5
	v_bitop3_b32 v6, v4, s4, v5 bitop3:0xde
	v_bitop3_b32 v147, v4, s19, v5 bitop3:0xde
	v_add_u32_e32 v147, 0x10000, v147
	v_lshlrev_b32_e32 v4, 14, v15
	v_and_b32_e32 v4, 0xffff8000, v4
	v_lshl_add_u32 v4, v14, 11, v4
	v_and_b32_e32 v5, 1, v15
	v_lshl_or_b32 v4, v5, 6, v4
	v_lshl_add_u32 v142, v16, 1, v4
	v_lshlrev_b32_e32 v4, 14, v2
	v_and_b32_e32 v4, 0xffff8000, v4
	v_lshl_add_u32 v4, v12, 11, v4
	v_and_b32_e32 v2, 1, v2
	v_readlane_b32 s20, v243, 43
	s_waitcnt vmcnt(6)
	v_lshl_or_b32 v2, v2, 6, v4
	v_mov_b32_e32 v4, v3
	v_mov_b32_e32 v5, v3
	v_readlane_b32 s21, v243, 44
	s_cmp_gt_i32 s18, 63
	v_lshl_add_u32 v144, v13, 1, v2
	v_mov_b32_e32 v2, v3
	v_add_u32_e32 v148, 0, v6
	v_mov_b64_e32 v[8:9], v[4:5]
	v_mov_b64_e32 v[12:13], v[4:5]
	v_mov_b64_e32 v[24:25], v[4:5]
	v_mov_b64_e32 v[28:29], v[4:5]
	v_mov_b64_e32 v[40:41], v[4:5]
	v_mov_b64_e32 v[44:45], v[4:5]
	v_mov_b64_e32 v[56:57], v[4:5]
	v_mov_b64_e32 v[60:61], v[4:5]
	v_mov_b64_e32 v[16:17], v[4:5]
	v_mov_b64_e32 v[20:21], v[4:5]
	v_mov_b64_e32 v[32:33], v[4:5]
	v_mov_b64_e32 v[36:37], v[4:5]
	v_mov_b64_e32 v[48:49], v[4:5]
	v_mov_b64_e32 v[52:53], v[4:5]
	v_mov_b64_e32 v[64:65], v[4:5]
	v_mov_b64_e32 v[68:69], v[4:5]
	v_mov_b64_e32 v[72:73], v[4:5]
	v_mov_b64_e32 v[76:77], v[4:5]
	v_mov_b64_e32 v[88:89], v[4:5]
	v_mov_b64_e32 v[92:93], v[4:5]
	v_mov_b64_e32 v[104:105], v[4:5]
	v_mov_b64_e32 v[108:109], v[4:5]
	v_mov_b64_e32 v[120:121], v[4:5]
	v_mov_b64_e32 v[124:125], v[4:5]
	v_mov_b64_e32 v[80:81], v[4:5]
	v_mov_b64_e32 v[84:85], v[4:5]
	v_mov_b64_e32 v[96:97], v[4:5]
	v_mov_b64_e32 v[100:101], v[4:5]
	v_mov_b64_e32 v[112:113], v[4:5]
	v_mov_b64_e32 v[116:117], v[4:5]
	v_mov_b64_e32 v[128:129], v[4:5]
	v_mov_b64_e32 v[132:133], v[4:5]
	s_mov_b32 s4, s20
	v_readlane_b32 s20, v243, 39
	s_cselect_b64 s[18:19], -1, 0
	s_add_i32 s59, s56, -2
	v_mov_b32_e32 v143, v3
	v_mov_b32_e32 v145, v3
	s_mov_b32 s60, 0
	v_mov_b64_e32 v[6:7], v[2:3]
	v_mov_b64_e32 v[10:11], v[2:3]
	v_mov_b64_e32 v[22:23], v[2:3]
	v_mov_b64_e32 v[26:27], v[2:3]
	v_mov_b64_e32 v[38:39], v[2:3]
	v_mov_b64_e32 v[42:43], v[2:3]
	v_mov_b64_e32 v[54:55], v[2:3]
	v_mov_b64_e32 v[58:59], v[2:3]
	v_mov_b64_e32 v[14:15], v[2:3]
	v_mov_b64_e32 v[18:19], v[2:3]
	v_mov_b64_e32 v[30:31], v[2:3]
	v_mov_b64_e32 v[34:35], v[2:3]
	v_mov_b64_e32 v[46:47], v[2:3]
	v_mov_b64_e32 v[50:51], v[2:3]
	v_mov_b64_e32 v[62:63], v[2:3]
	v_mov_b64_e32 v[66:67], v[2:3]
	v_mov_b64_e32 v[70:71], v[2:3]
	v_mov_b64_e32 v[74:75], v[2:3]
	v_mov_b64_e32 v[86:87], v[2:3]
	v_mov_b64_e32 v[90:91], v[2:3]
	v_mov_b64_e32 v[102:103], v[2:3]
	v_mov_b64_e32 v[106:107], v[2:3]
	v_mov_b64_e32 v[118:119], v[2:3]
	v_mov_b64_e32 v[122:123], v[2:3]
	v_mov_b64_e32 v[78:79], v[2:3]
	v_mov_b64_e32 v[82:83], v[2:3]
	v_mov_b64_e32 v[94:95], v[2:3]
	v_mov_b64_e32 v[98:99], v[2:3]
	v_mov_b64_e32 v[110:111], v[2:3]
	v_mov_b64_e32 v[114:115], v[2:3]
	v_mov_b64_e32 v[126:127], v[2:3]
	v_mov_b64_e32 v[130:131], v[2:3]
	s_mov_b32 s61, s20
	s_barrier
	v_readlane_b32 s21, v243, 40
	s_branch .LBB0_1920

; #define LAS __attribute__((address_space(3)))
; #define PG8_WAIT_V(n) asm volatile("s_waitcnt vmcnt(" #n ")" ::: "memory")
; #define PG8_BAR __builtin_amdgcn_s_barrier()
; template <class Epi, bool ALIGN_EPI = true>
; __device__ __forceinline__ void gemm_phase(LAS unsigned char* lds, const Gemm g, const Sched& S, const Epi& E) {
;     ...
;     for (int i = 0; i < 2; ++i) { int R, C; stage_rc(tid * 16 + i * 8192, R, C); const int Rb = (R & ~31) + perm32(R & 31);
;         voffA[i] = (unsigned)(R * g.lda + C) * 2u; voffB[i] = (unsigned)(Rb * g.ldb + C) * 2u; }
;     const size_t kstep = (size_t)(BK * 2);
;     const size_t hstepA = (size_t)HALF * g.lda * 2, hstepB = (size_t)HALF * g.ldb * 2;
;     const unsigned ldsw = (unsigned)wid * 1024u;
;     const int aoff = lds_byte(wr * 64 + fr, fq * 8), boff = lds_byte(wc * 32 + fr, fq * 8);
;     ...
;     Unit cur, nxt; int ui = 0;
;     if (!S.next(0, cur)) return;
;     if constexpr (Epi::USES_RSTD) {
;         LAS float* T = (LAS float*)(lds + RSTD_OFF);
; #pragma unroll
;         for (int k = 0; k < RSTD_UNITS * 256 / 512; ++k) { const int idx = tid + 512 * k; Unit uu;
;             if (S.next(idx >> 8, uu)) { const float* sp = E.SS + uu.pm * BM + (idx & 255); float ssum = 0.f;
; #pragma unroll
;                 for (int j = 0; j < 8; ++j) ssum += sp[(size_t)j * MROWS];
;                 T[idx] = __builtin_amdgcn_rsqf(ssum * (1.0f / DM) + EPS); } }
;         asm volatile("s_waitcnt lgkmcnt(0)" ::: "memory"); __builtin_amdgcn_s_barrier(); asm volatile("" ::: "memory");
;     }
;     f32x4 acc[2][2][4][2];
; #pragma unroll
;     for (int a = 0; a < 2; ++a)
; #pragma unroll
;         for (int b = 0; b < 2; ++b)
; #pragma unroll
;             for (int m = 0; m < 4; ++m)
; #pragma unroll
;                 for (int n = 0; n < 2; ++n) acc[a][b][m][n] = (f32x4){0.f, 0.f, 0.f, 0.f};
;     bf16x8 At[4][2], B0[2][2], B1[2][2];
;     const char* cA = (const char*)g.A + cur.aoff; const char* cB = (const char*)g.Bt + cur.boff;
;     PG8_STAGE(PG8_SB(0, 0), cB, voffB); PG8_STAGE(PG8_SB(0, 1), cB + hstepB, voffB); PG8_STAGE(PG8_SA(0, 0), cA, voffA); PG8_STAGE(PG8_SA(0, 1), cA + hstepA, voffA);
;     if (wr == 1) PG8_BAR;
;     PG8_WAIT_V(2); PG8_BAR;
;     PG8_STAGE(PG8_SB(1, 0), cB + kstep, voffB); PG8_STAGE(PG8_SA(1, 0), cA + kstep, voffA); PG8_STAGE(PG8_SB(1, 1), cB + hstepB + kstep, voffB);
;     PG8_WAIT_V(6); PG8_BAR;
.LBB0_2015:
	s_add_u32 s52, s54, s14
	s_addc_u32 s53, s55, s15
	s_ashr_i32 s14, s16, 31
	s_lshr_b32 s14, s14, 26
	s_and_b32 s20, s17, 3
	s_add_i32 s14, s16, s14
	s_add_i32 m0, s36, 0x18000
	v_lshl_add_u64 v[10:11], v[10:11], 0, s[8:9]
	s_ashr_i32 s54, s14, 6
	s_lshl_b32 s55, s19, 6
	s_lshl_b32 s17, s19, 13
	s_lshl_b32 s19, s20, 12
	global_load_lds_dwordx4 v[10:11], off
	v_lshl_add_u64 v[8:9], v[8:9], 0, s[8:9]
	s_add_i32 m0, s36, 0x1a000
	s_add_i32 s56, s36, 0x8000
	s_add_i32 s57, s36, 0xa000
	global_load_lds_dwordx4 v[8:9], off
	v_lshl_add_u64 v[4:5], v[4:5], 0, s[8:9]
	s_mov_b32 m0, s56
	s_add_u32 s14, s0, 0x80080
	global_load_lds_dwordx4 v[4:5], off
	v_lshl_add_u64 v[4:5], v[6:7], 0, s[8:9]
	s_mov_b32 m0, s57
	s_addc_u32 s15, s1, 0
	global_load_lds_dwordx4 v[4:5], off
	s_add_i32 m0, s36, 0x1c000
	v_lshl_add_u64 v[4:5], s[14:15], 0, v[136:137]
	global_load_lds_dwordx4 v[4:5], off
	v_lshl_add_u64 v[4:5], s[14:15], 0, v[140:141]
	s_add_i32 m0, s36, 0x1e000
	s_movk_i32 s10, 0x3c0
	global_load_lds_dwordx4 v[4:5], off
	s_waitcnt vmcnt(8)
	s_barrier
	v_and_b32_e32 v4, 48, v12
	v_lshlrev_b32_e32 v5, 6, v12
	v_and_or_b32 v4, v5, s10, v4
	v_lshlrev_b32_e32 v5, 2, v12
	v_and_b32_e32 v5, 32, v5
	v_bitop3_b32 v6, v4, s17, v5 bitop3:0xde
	v_bitop3_b32 v151, v4, s19, v5 bitop3:0xde
	v_add_u32_e32 v151, 0x10000, v151
	v_lshlrev_b32_e32 v4, 15, v2
	v_and_b32_e32 v4, 0xffff0000, v4
	s_cmp_gt_i32 s16, 63
	v_lshl_add_u32 v4, v13, 12, v4
	v_and_b32_e32 v2, 1, v2
	s_cselect_b64 s[14:15], -1, 0
	s_add_i32 s58, s54, -2
	v_lshl_or_b32 v2, v2, 6, v4
	s_cmpk_lt_u32 s18, 0x100
	v_lshl_add_u32 v142, v14, 1, v2
	v_lshlrev_b32_e32 v2, 15, v15
	s_cselect_b64 s[16:17], -1, 0
	s_and_b32 s18, s18, 0xffffff00
	v_and_b32_e32 v2, 0xffff0000, v2
	s_add_i32 s60, s18, 0
	v_lshl_add_u32 v2, v16, 12, v2
	v_and_b32_e32 v4, 1, v15
	v_readlane_b32 s18, v243, 55
	s_waitcnt vmcnt(6)
	v_lshl_or_b32 v2, v4, 6, v2
	v_mov_b32_e32 v4, v3
	v_mov_b32_e32 v5, v3
	v_readlane_b32 s19, v243, 56
	v_and_b32_e32 v150, 63, v12
	v_lshl_add_u32 v144, v17, 1, v2
	v_mov_b32_e32 v2, v3
	v_add_u32_e32 v152, 0, v6
	v_mov_b64_e32 v[8:9], v[4:5]
	v_mov_b64_e32 v[12:13], v[4:5]
	v_mov_b64_e32 v[16:17], v[4:5]
	v_mov_b64_e32 v[20:21], v[4:5]
	v_mov_b64_e32 v[24:25], v[4:5]
	v_mov_b64_e32 v[28:29], v[4:5]
	v_mov_b64_e32 v[32:33], v[4:5]
	v_mov_b64_e32 v[36:37], v[4:5]
	v_mov_b64_e32 v[40:41], v[4:5]
	v_mov_b64_e32 v[44:45], v[4:5]
	v_mov_b64_e32 v[48:49], v[4:5]
	v_mov_b64_e32 v[52:53], v[4:5]
	v_mov_b64_e32 v[56:57], v[4:5]
	v_mov_b64_e32 v[60:61], v[4:5]
	v_mov_b64_e32 v[64:65], v[4:5]
	v_mov_b64_e32 v[68:69], v[4:5]
	v_mov_b64_e32 v[72:73], v[4:5]
	v_mov_b64_e32 v[76:77], v[4:5]
	v_mov_b64_e32 v[80:81], v[4:5]
	v_mov_b64_e32 v[84:85], v[4:5]
	v_mov_b64_e32 v[88:89], v[4:5]
	v_mov_b64_e32 v[92:93], v[4:5]
	v_mov_b64_e32 v[96:97], v[4:5]
	v_mov_b64_e32 v[100:101], v[4:5]
	v_mov_b64_e32 v[104:105], v[4:5]
	v_mov_b64_e32 v[108:109], v[4:5]
	v_mov_b64_e32 v[112:113], v[4:5]
	v_mov_b64_e32 v[116:117], v[4:5]
	v_mov_b64_e32 v[120:121], v[4:5]
	v_mov_b64_e32 v[124:125], v[4:5]
	v_mov_b64_e32 v[128:129], v[4:5]
	v_mov_b64_e32 v[132:133], v[4:5]
	s_mov_b32 s62, s18
	v_readlane_b32 s18, v243, 51
	s_lshl_b32 s59, s20, 6
	s_add_i32 s60, s60, 0x20000
	v_mov_b32_e32 v143, v3
	v_mov_b32_e32 v145, v3
	s_mov_b32 s61, 0
	v_mov_b64_e32 v[6:7], v[2:3]
	v_mov_b64_e32 v[10:11], v[2:3]
	v_mov_b64_e32 v[14:15], v[2:3]
	v_mov_b64_e32 v[18:19], v[2:3]
	v_mov_b64_e32 v[22:23], v[2:3]
	v_mov_b64_e32 v[26:27], v[2:3]
	v_mov_b64_e32 v[30:31], v[2:3]
	v_mov_b64_e32 v[34:35], v[2:3]
	v_mov_b64_e32 v[38:39], v[2:3]
	v_mov_b64_e32 v[42:43], v[2:3]
	v_mov_b64_e32 v[46:47], v[2:3]
	v_mov_b64_e32 v[50:51], v[2:3]
	v_mov_b64_e32 v[54:55], v[2:3]
	v_mov_b64_e32 v[58:59], v[2:3]
	v_mov_b64_e32 v[62:63], v[2:3]
	v_mov_b64_e32 v[66:67], v[2:3]
	v_mov_b64_e32 v[70:71], v[2:3]
	v_mov_b64_e32 v[74:75], v[2:3]
	v_mov_b64_e32 v[78:79], v[2:3]
	v_mov_b64_e32 v[82:83], v[2:3]
	v_mov_b64_e32 v[86:87], v[2:3]
	v_mov_b64_e32 v[90:91], v[2:3]
	v_mov_b64_e32 v[94:95], v[2:3]
	v_mov_b64_e32 v[98:99], v[2:3]
	v_mov_b64_e32 v[102:103], v[2:3]
	v_mov_b64_e32 v[106:107], v[2:3]
	v_mov_b64_e32 v[110:111], v[2:3]
	v_mov_b64_e32 v[114:115], v[2:3]
	v_mov_b64_e32 v[118:119], v[2:3]
	v_mov_b64_e32 v[122:123], v[2:3]
	v_mov_b64_e32 v[126:127], v[2:3]
	v_mov_b64_e32 v[130:131], v[2:3]
	s_mov_b32 s63, s18
	s_barrier
	v_readlane_b32 s19, v243, 52
	s_branch .LBB0_2018

; #define LAS __attribute__((address_space(3)))
; #define PG8_WAIT_V(n) asm volatile("s_waitcnt vmcnt(" #n ")" ::: "memory")
; #define PG8_BAR __builtin_amdgcn_s_barrier()
; template <class Epi, bool ALIGN_EPI = true>
; __device__ __forceinline__ void gemm_phase(LAS unsigned char* lds, const Gemm g, const Sched& S, const Epi& E) {
;     ...
;     for (int i = 0; i < 2; ++i) { int R, C; stage_rc(tid * 16 + i * 8192, R, C); const int Rb = (R & ~31) + perm32(R & 31);
;         voffA[i] = (unsigned)(R * g.lda + C) * 2u; voffB[i] = (unsigned)(Rb * g.ldb + C) * 2u; }
;     const size_t kstep = (size_t)(BK * 2);
;     const size_t hstepA = (size_t)HALF * g.lda * 2, hstepB = (size_t)HALF * g.ldb * 2;
;     const unsigned ldsw = (unsigned)wid * 1024u;
;     const int aoff = lds_byte(wr * 64 + fr, fq * 8), boff = lds_byte(wc * 32 + fr, fq * 8);
;     ...
;     Unit cur, nxt; int ui = 0;
;     if (!S.next(0, cur)) return;
;     if constexpr (Epi::USES_RSTD) {
;         LAS float* T = (LAS float*)(lds + RSTD_OFF);
; #pragma unroll
;         for (int k = 0; k < RSTD_UNITS * 256 / 512; ++k) { const int idx = tid + 512 * k; Unit uu;
;             if (S.next(idx >> 8, uu)) { const float* sp = E.SS + uu.pm * BM + (idx & 255); float ssum = 0.f;
; #pragma unroll
;                 for (int j = 0; j < 8; ++j) ssum += sp[(size_t)j * MROWS];
;                 T[idx] = __builtin_amdgcn_rsqf(ssum * (1.0f / DM) + EPS); } }
;         asm volatile("s_waitcnt lgkmcnt(0)" ::: "memory"); __builtin_amdgcn_s_barrier(); asm volatile("" ::: "memory");
;     }
;     f32x4 acc[2][2][4][2];
; #pragma unroll
;     for (int a = 0; a < 2; ++a)
; #pragma unroll
;         for (int b = 0; b < 2; ++b)
; #pragma unroll
;             for (int m = 0; m < 4; ++m)
; #pragma unroll
;                 for (int n = 0; n < 2; ++n) acc[a][b][m][n] = (f32x4){0.f, 0.f, 0.f, 0.f};
;     bf16x8 At[4][2], B0[2][2], B1[2][2];
;     const char* cA = (const char*)g.A + cur.aoff; const char* cB = (const char*)g.Bt + cur.boff;
;     PG8_STAGE(PG8_SB(0, 0), cB, voffB); PG8_STAGE(PG8_SB(0, 1), cB + hstepB, voffB); PG8_STAGE(PG8_SA(0, 0), cA, voffA); PG8_STAGE(PG8_SA(0, 1), cA + hstepA, voffA);
;     if (wr == 1) PG8_BAR;
;     PG8_WAIT_V(2); PG8_BAR;
;     PG8_STAGE(PG8_SB(1, 0), cB + kstep, voffB); PG8_STAGE(PG8_SA(1, 0), cA + kstep, voffA); PG8_STAGE(PG8_SB(1, 1), cB + hstepB + kstep, voffB);
;     PG8_WAIT_V(6); PG8_BAR;
.LBB0_2276:
	s_ashr_i32 s19, s18, 31
	s_lshr_b32 s19, s19, 26
	s_and_b32 s5, s5, 3
	s_add_i32 s19, s18, s19
	s_add_i32 m0, s50, 0x18000
	v_lshl_add_u64 v[10:11], v[10:11], 0, s[8:9]
	s_ashr_i32 s54, s19, 6
	s_lshl_b32 s31, s4, 6
	s_lshl_b32 s4, s4, 13
	s_lshl_b32 s19, s5, 12
	global_load_lds_dwordx4 v[10:11], off
	v_lshl_add_u64 v[8:9], v[8:9], 0, s[8:9]
	s_add_i32 m0, s50, 0x1a000
	s_add_i32 s55, s50, 0x8000
	s_add_i32 s56, s50, 0xa000
	global_load_lds_dwordx4 v[8:9], off
	v_lshl_add_u64 v[6:7], v[6:7], 0, s[8:9]
	s_mov_b32 m0, s55
	s_add_u32 s20, s14, 0x160080
	global_load_lds_dwordx4 v[6:7], off
	v_lshl_add_u64 v[4:5], v[4:5], 0, s[8:9]
	s_mov_b32 m0, s56
	s_addc_u32 s21, s15, 0
	global_load_lds_dwordx4 v[4:5], off
	s_add_i32 m0, s50, 0x1c000
	v_lshl_add_u64 v[4:5], s[20:21], 0, v[138:139]
	global_load_lds_dwordx4 v[4:5], off
	v_lshl_add_u64 v[4:5], s[20:21], 0, v[134:135]
	s_add_i32 m0, s50, 0x1e000
	s_movk_i32 s10, 0x3c0
	global_load_lds_dwordx4 v[4:5], off
	s_waitcnt vmcnt(8)
	s_barrier
	v_and_b32_e32 v4, 48, v146
	v_lshlrev_b32_e32 v5, 6, v146
	v_and_or_b32 v4, v5, s10, v4
	v_lshlrev_b32_e32 v5, 2, v146
	v_and_b32_e32 v5, 32, v5
	s_movk_i32 s10, 0x1600
	v_bitop3_b32 v6, v4, s4, v5 bitop3:0xde
	v_bitop3_b32 v147, v4, s19, v5 bitop3:0xde
	v_add_u32_e32 v147, 0x10000, v147
	v_lshrrev_b32_e32 v4, 1, v16
	v_mul_lo_u32 v2, v2, s10
	s_mov_b32 s4, 0x16000
	v_mad_u64_u32 v[4:5], s[20:21], v4, s4, v[2:3]
	v_or_b32_e32 v2, v4, v17
	v_add_lshl_u32 v2, v2, v18, 1
	s_mov_b64 s[22:23], 0x160080
	v_lshl_add_u64 v[142:143], v[2:3], 0, s[22:23]
	v_lshrrev_b32_e32 v4, 1, v12
	v_mul_lo_u32 v2, v13, s10
	v_mad_u64_u32 v[4:5], s[20:21], v4, s4, v[2:3]
	v_or_b32_e32 v2, v4, v14
	v_readlane_b32 s20, v243, 43
	s_waitcnt vmcnt(6)
	v_add_lshl_u32 v2, v2, v15, 1
	v_mov_b32_e32 v4, v3
	v_mov_b32_e32 v5, v3
	v_readlane_b32 s21, v243, 44
	s_cmp_gt_i32 s18, 63
	v_lshl_add_u64 v[144:145], v[2:3], 0, s[22:23]
	v_mov_b32_e32 v2, v3
	v_add_u32_e32 v148, 0, v6
	v_mov_b64_e32 v[8:9], v[4:5]
	v_mov_b64_e32 v[12:13], v[4:5]
	v_mov_b64_e32 v[24:25], v[4:5]
	v_mov_b64_e32 v[28:29], v[4:5]
	v_mov_b64_e32 v[40:41], v[4:5]
	v_mov_b64_e32 v[44:45], v[4:5]
	v_mov_b64_e32 v[56:57], v[4:5]
	v_mov_b64_e32 v[60:61], v[4:5]
	v_mov_b64_e32 v[16:17], v[4:5]
	v_mov_b64_e32 v[20:21], v[4:5]
	v_mov_b64_e32 v[32:33], v[4:5]
	v_mov_b64_e32 v[36:37], v[4:5]
	v_mov_b64_e32 v[48:49], v[4:5]
	v_mov_b64_e32 v[52:53], v[4:5]
	v_mov_b64_e32 v[64:65], v[4:5]
	v_mov_b64_e32 v[68:69], v[4:5]
	v_mov_b64_e32 v[72:73], v[4:5]
	v_mov_b64_e32 v[76:77], v[4:5]
	v_mov_b64_e32 v[88:89], v[4:5]
	v_mov_b64_e32 v[92:93], v[4:5]
	v_mov_b64_e32 v[104:105], v[4:5]
	v_mov_b64_e32 v[108:109], v[4:5]
	v_mov_b64_e32 v[120:121], v[4:5]
	v_mov_b64_e32 v[124:125], v[4:5]
	v_mov_b64_e32 v[80:81], v[4:5]
	v_mov_b64_e32 v[84:85], v[4:5]
	v_mov_b64_e32 v[96:97], v[4:5]
	v_mov_b64_e32 v[100:101], v[4:5]
	v_mov_b64_e32 v[112:113], v[4:5]
	v_mov_b64_e32 v[116:117], v[4:5]
	v_mov_b64_e32 v[128:129], v[4:5]
	v_mov_b64_e32 v[132:133], v[4:5]
	s_mov_b32 s4, s20
	v_readlane_b32 s20, v243, 39
	s_cselect_b64 s[18:19], -1, 0
	s_add_i32 s57, s54, -2
	s_mov_b32 s58, 0
	v_mov_b64_e32 v[6:7], v[2:3]
	v_mov_b64_e32 v[10:11], v[2:3]
	v_mov_b64_e32 v[22:23], v[2:3]
	v_mov_b64_e32 v[26:27], v[2:3]
	v_mov_b64_e32 v[38:39], v[2:3]
	v_mov_b64_e32 v[42:43], v[2:3]
	v_mov_b64_e32 v[54:55], v[2:3]
	v_mov_b64_e32 v[58:59], v[2:3]
	v_mov_b64_e32 v[14:15], v[2:3]
	v_mov_b64_e32 v[18:19], v[2:3]
	v_mov_b64_e32 v[30:31], v[2:3]
	v_mov_b64_e32 v[34:35], v[2:3]
	v_mov_b64_e32 v[46:47], v[2:3]
	v_mov_b64_e32 v[50:51], v[2:3]
	v_mov_b64_e32 v[62:63], v[2:3]
	v_mov_b64_e32 v[66:67], v[2:3]
	v_mov_b64_e32 v[70:71], v[2:3]
	v_mov_b64_e32 v[74:75], v[2:3]
	v_mov_b64_e32 v[86:87], v[2:3]
	v_mov_b64_e32 v[90:91], v[2:3]
	v_mov_b64_e32 v[102:103], v[2:3]
	v_mov_b64_e32 v[106:107], v[2:3]
	v_mov_b64_e32 v[118:119], v[2:3]
	v_mov_b64_e32 v[122:123], v[2:3]
	v_mov_b64_e32 v[78:79], v[2:3]
	v_mov_b64_e32 v[82:83], v[2:3]
	v_mov_b64_e32 v[94:95], v[2:3]
	v_mov_b64_e32 v[98:99], v[2:3]
	v_mov_b64_e32 v[110:111], v[2:3]
	v_mov_b64_e32 v[114:115], v[2:3]
	v_mov_b64_e32 v[126:127], v[2:3]
	v_mov_b64_e32 v[130:131], v[2:3]
	v_readlane_b32 s21, v243, 40
	s_mov_b32 s59, s20
	s_barrier
	s_branch .LBB0_2278
